# diff attention fast path checks the running max per lane (no cross-lane reduction unless the max moves), permlane16/32 swaps for the rare update path
# speedup vs baseline: 1.0215x; 1.0039x over previous
.LBB0_785:
	s_lshr_b32 s52, s51, 1
	s_lshl_b32 s2, s52, 7
	v_readlane_b32 s3, v251, 38
	s_add_i32 s4, s3, s2
	s_lshl_b64 s[34:35], s[4:5], 1
	s_bitcmp0_b32 s51, 0
	v_readlane_b32 s2, v251, 34
	v_readlane_b32 s3, v251, 36
	s_cselect_b32 s3, s3, s2
	v_readlane_b32 s60, v251, 32
	v_readlane_b32 s61, v251, 33
	s_or_b32 s2, s60, s3
	s_mul_i32 s30, s61, 0x3000
	s_mul_hi_u32 s4, s2, 0x3000
	v_writelane_b32 v251, s30, 44
	s_add_i32 s4, s4, s30
	s_mul_i32 s30, s2, 0x3000
	s_add_u32 s30, s48, s30
	s_addc_u32 s4, s49, s4
	s_add_u32 s38, s30, s34
	s_addc_u32 s39, s4, s35
	s_add_u32 s36, s40, s34
	v_readfirstlane_b32 s4, v208
	s_addc_u32 s37, s41, s35
	s_ashr_i32 s56, s4, 6
	s_and_b32 s4, s4, 0x3fffffc0
	s_lshl_b32 s4, s4, 2
	s_lshl_b32 s31, s56, 3
	s_lshl_b32 s30, s56, 5
	s_add_i32 s4, s4, 0
	v_or_b32_e32 v0, s31, v212
	v_bitop3_b32 v7, s31, v229, v214 bitop3:0xc8
	s_lshl_b32 s31, s56, 2
	s_add_i32 s57, s4, 0x18000
	s_add_i32 s4, s30, s3
	s_and_b32 s58, s31, 4
	s_lshl_b32 s53, s56, 11
	s_lshl_b32 s54, s56, 12
	s_ashr_i32 s31, s30, 31
	s_mul_i32 s55, s56, 0x60000
	s_mul_hi_i32 s59, s30, 0x3000
	s_add_u32 s38, s38, s55
	v_or3_b32 v2, v215, v7, s58
	s_addc_u32 s39, s39, s59
	s_lshr_b32 s3, s3, 6
	v_mul_lo_u32 v2, v2, s45
	s_or_b32 s55, s3, 3
	v_or_b32_e32 v8, v2, v216
	v_lshl_add_u64 v[2:3], s[38:39], 0, v[194:195]
	s_mov_b64 s[38:39], 0x30000
	s_cmp_lg_u32 0, -1
	v_lshl_add_u64 v[4:5], v[2:3], 0, s[38:39]
	s_movk_i32 s38, 0x1000
	s_cselect_b32 s3, 0, 0
	v_mul_lo_u32 v0, v0, s44
	s_add_i32 s38, s3, s53
	v_or_b32_e32 v6, v0, v213
	v_or_b32_e32 v0, v0, v228
	global_load_dwordx4 v[162:165], v[2:3], off
	global_load_dwordx4 v[166:169], v[2:3], off offset:64
	global_load_dwordx4 v[170:173], v[2:3], off offset:128
	global_load_dwordx4 v[174:177], v[2:3], off offset:192
	global_load_dwordx4 v[178:181], v[4:5], off
	global_load_dwordx4 v[182:185], v[4:5], off offset:64
	global_load_dwordx4 v[186:189], v[4:5], off offset:128
	global_load_dwordx4 v[190:193], v[4:5], off offset:192
	s_add_i32 m0, s38, 0x10000
	v_add_u32_e32 v0, 0xc000, v0
	global_load_lds_dwordx4 v6, s[36:37]
	s_add_i32 m0, s38, 0x10400
	s_add_i32 s3, s54, s3
	global_load_lds_dwordx4 v0, s[36:37]
	s_mul_i32 s73, s56, 0x18000
	v_add_u32_e32 v0, s73, v220
	v_lshl_add_u64 v[2:3], s[8:9], 0, v[0:1]
	s_mov_b32 m0, s3
	s_mov_b64 s[36:37], 0x80
	global_load_lds_dwordx4 v0, s[8:9]
	v_lshl_add_u64 v[4:5], v[2:3], 0, s[36:37]
	s_add_i32 m0, s3, 0x400
	s_mov_b64 s[36:37], 0x100
	global_load_lds_dwordx4 v[4:5], off
	v_lshl_add_u64 v[4:5], v[2:3], 0, s[36:37]
	s_add_i32 m0, s3, 0x800
	s_mov_b64 s[36:37], 0x180
	global_load_lds_dwordx4 v[4:5], off
	v_lshl_add_u64 v[2:3], v[2:3], 0, s[36:37]
	s_add_i32 m0, s3, 0xc00
	v_add3_u32 v0, v215, v7, s58
	global_load_lds_dwordx4 v[2:3], off
	v_mul_lo_u32 v0, v0, s45
	v_or_b32_e32 v0, v216, v0
	v_readlane_b32 s36, v251, 40
	v_lshlrev_b32_e32 v0, 1, v0
	v_readlane_b32 s37, v251, 41
	s_mul_i32 s56, s56, 0x18000
	v_mov_b32_e32 v14, v1
	v_add_u32_e32 v0, s56, v220
	v_lshl_add_u64 v[196:197], s[36:37], 0, v[0:1]
	v_add3_u32 v0, v226, s56, v228
	v_lshl_add_u64 v[198:199], s[34:35], 0, v[0:1]
	v_add_u32_e32 v0, s56, v227
	v_mov_b32_e32 v15, v1
	s_waitcnt vmcnt(0)
	v_lshl_add_u64 v[200:201], s[34:35], 0, v[0:1]
	v_mov_b32_e32 v0, v1
	v_mov_b32_e32 v2, v1
	v_mov_b32_e32 v3, v1
	v_mov_b32_e32 v4, v1
	v_mov_b32_e32 v5, v1
	v_mov_b32_e32 v6, v1
	v_mov_b32_e32 v7, v1
	v_mov_b32_e32 v8, v1
	v_mov_b32_e32 v9, v1
	v_mov_b32_e32 v10, v1
	v_mov_b32_e32 v11, v1
	v_mov_b32_e32 v12, v1
	v_mov_b32_e32 v13, v1
	s_waitcnt vmcnt(0)
	v_mov_b64_e32 v[128:129], v[14:15]
	v_mov_b64_e32 v[112:113], v[14:15]
	v_mov_b64_e32 v[96:97], v[14:15]
	v_mov_b64_e32 v[80:81], v[14:15]
	v_mov_b64_e32 v[64:65], v[14:15]
	v_mov_b64_e32 v[48:49], v[14:15]
	v_mov_b64_e32 v[32:33], v[14:15]
	v_mov_b64_e32 v[126:127], v[12:13]
	v_mov_b64_e32 v[124:125], v[10:11]
	v_mov_b64_e32 v[122:123], v[8:9]
	v_mov_b64_e32 v[120:121], v[6:7]
	v_mov_b64_e32 v[118:119], v[4:5]
	v_mov_b64_e32 v[116:117], v[2:3]
	v_mov_b64_e32 v[114:115], v[0:1]
	v_mov_b64_e32 v[110:111], v[12:13]
	v_mov_b64_e32 v[108:109], v[10:11]
	v_mov_b64_e32 v[106:107], v[8:9]
	v_mov_b64_e32 v[104:105], v[6:7]
	v_mov_b64_e32 v[102:103], v[4:5]
	v_mov_b64_e32 v[100:101], v[2:3]
	v_mov_b64_e32 v[98:99], v[0:1]
	v_mov_b64_e32 v[94:95], v[12:13]
	v_mov_b64_e32 v[92:93], v[10:11]
	v_mov_b64_e32 v[90:91], v[8:9]
	v_mov_b64_e32 v[88:89], v[6:7]
	v_mov_b64_e32 v[86:87], v[4:5]
	v_mov_b64_e32 v[84:85], v[2:3]
	v_mov_b64_e32 v[82:83], v[0:1]
	v_mov_b64_e32 v[78:79], v[12:13]
	v_mov_b64_e32 v[76:77], v[10:11]
	v_mov_b64_e32 v[74:75], v[8:9]
	v_mov_b64_e32 v[72:73], v[6:7]
	v_mov_b64_e32 v[70:71], v[4:5]
	v_mov_b64_e32 v[68:69], v[2:3]
	v_mov_b64_e32 v[66:67], v[0:1]
	v_mov_b64_e32 v[62:63], v[12:13]
	v_mov_b64_e32 v[60:61], v[10:11]
	v_mov_b64_e32 v[58:59], v[8:9]
	v_mov_b64_e32 v[56:57], v[6:7]
	v_mov_b64_e32 v[54:55], v[4:5]
	v_mov_b64_e32 v[52:53], v[2:3]
	v_mov_b64_e32 v[50:51], v[0:1]
	v_mov_b64_e32 v[46:47], v[12:13]
	v_mov_b64_e32 v[44:45], v[10:11]
	v_mov_b64_e32 v[42:43], v[8:9]
	v_mov_b64_e32 v[40:41], v[6:7]
	v_mov_b64_e32 v[38:39], v[4:5]
	v_mov_b64_e32 v[36:37], v[2:3]
	v_mov_b64_e32 v[34:35], v[0:1]
	v_mov_b64_e32 v[30:31], v[12:13]
	v_mov_b64_e32 v[28:29], v[10:11]
	v_mov_b64_e32 v[26:27], v[8:9]
	v_mov_b64_e32 v[24:25], v[6:7]
	v_mov_b64_e32 v[22:23], v[4:5]
	v_mov_b64_e32 v[20:21], v[2:3]
	v_mov_b64_e32 v[18:19], v[0:1]
	v_mov_b64_e32 v[16:17], v[14:15]
	s_mov_b32 s3, s61
	v_add_u32_e32 v233, s4, v221
	v_and_b32_e32 v232, 15, v209
	v_lshl_add_u32 v232, v232, 2, s57
	v_lshl_add_u32 v231, v212, 4, s57
	v_mov_b32_e32 v237, 0xf149f2ca
	s_movk_i32 s56, 0x7f
	s_mov_b64 s[34:35], s[6:7]
	s_mov_b32 s57, 2
	v_mov_b64_e32 v[14:15], v[12:13]
	v_mov_b64_e32 v[12:13], v[10:11]
	v_mov_b64_e32 v[10:11], v[8:9]
	v_mov_b64_e32 v[8:9], v[6:7]
	v_mov_b64_e32 v[6:7], v[4:5]
	v_mov_b64_e32 v[4:5], v[2:3]
	v_mov_b64_e32 v[2:3], v[0:1]
	v_mov_b32_e32 v0, 0
	v_mov_b32_e32 v222, 0xf149f2ca
	v_mov_b32_e32 v223, 0
	v_mov_b32_e32 v225, 0xf149f2ca
	v_mov_b32_e32 v236, 0xf149f2ca
	s_waitcnt lgkmcnt(0)
	s_barrier
	s_branch .LBB0_788

.Ld16a_nm0:
	v_max3_f32 v234, v130, v131, v132
	v_max3_f32 v234, v234, v133, v134
	v_max3_f32 v234, v234, v135, v136
	v_max3_f32 v234, v234, v137, v138
	v_max3_f32 v234, v234, v139, v140
	v_max3_f32 v234, v234, v141, v142
	v_max3_f32 v234, v234, v143, v144
	v_max_f32_e32 v234, v234, v145
	v_max3_f32 v235, v146, v147, v148
	v_max3_f32 v235, v235, v149, v150
	v_max3_f32 v235, v235, v151, v152
	v_max3_f32 v235, v235, v153, v154
	v_max3_f32 v235, v235, v155, v156
	v_max3_f32 v235, v235, v157, v158
	v_max3_f32 v235, v235, v159, v160
	v_max_f32_e32 v235, v235, v161
	v_cmp_ge_f32_e32 vcc, v225, v234
	v_cmp_ge_f32_e64 s[74:75], v236, v235
	s_nop 3
	s_and_b64 vcc, vcc, s[74:75]
	s_cmp_eq_u64 vcc, exec
	s_cbranch_scc0 .Ld16a_sl0

.Ld16a_sl0:
	v_mov_b32_e32 v246, v234
	v_mov_b32_e32 v247, v235
	s_nop 1
	v_permlane16_swap_b32_e32 v234, v246
	v_permlane16_swap_b32_e32 v235, v247
	v_max_f32_e32 v234, v234, v246
	v_max_f32_e32 v235, v235, v247
	v_mov_b32_e32 v246, v234
	v_mov_b32_e32 v247, v235
	s_nop 1
	v_permlane32_swap_b32_e32 v234, v246
	v_permlane32_swap_b32_e32 v235, v247
	v_max_f32_e32 v234, v234, v246
	v_max_f32_e32 v235, v235, v247
	v_max_f32_e32 v234, v237, v234
	v_max_f32_e32 v235, v222, v235
	v_sub_f32_e32 v246, v237, v234
	v_sub_f32_e32 v247, v222, v235
	v_mul_f32_e32 v246, 0x3e0293ee, v246
	v_mul_f32_e32 v247, 0x3e0293ee, v247
	v_exp_f32_e32 v246, v246
	v_exp_f32_e32 v247, v247
	v_mov_b32_e32 v237, v234
	v_mov_b32_e32 v222, v235
	v_mul_f32_e32 v210, 0xbe0293ee, v234
	v_mul_f32_e32 v211, 0xbe0293ee, v235
	v_add_f32_e32 v225, 0x42b504f3, v234
	v_add_f32_e32 v236, 0x42b504f3, v235
	v_mul_f32_e32 v0, v0, v246
	v_mul_f32_e32 v223, v223, v247
	s_and_saveexec_b64 s[76:77], s[0:1]
	ds_write_b32 v232, v246 offset:128
	ds_write_b32 v232, v247 offset:192
	s_or_b64 exec, exec, s[76:77]
	s_waitcnt lgkmcnt(0)
	ds_read_b128 v[238:241], v231 offset:128
	ds_read_b128 v[242:245], v231 offset:192
	s_waitcnt lgkmcnt(0)
	v_pk_mul_f32 v[2:3], v[2:3], v[238:239]
	v_pk_mul_f32 v[4:5], v[4:5], v[240:241]
	v_pk_mul_f32 v[6:7], v[6:7], v[238:239]
	v_pk_mul_f32 v[8:9], v[8:9], v[240:241]
	v_pk_mul_f32 v[10:11], v[10:11], v[238:239]
	v_pk_mul_f32 v[12:13], v[12:13], v[240:241]
	v_pk_mul_f32 v[14:15], v[14:15], v[238:239]
	v_pk_mul_f32 v[16:17], v[16:17], v[240:241]
	v_pk_mul_f32 v[18:19], v[18:19], v[238:239]
	v_pk_mul_f32 v[20:21], v[20:21], v[240:241]
	v_pk_mul_f32 v[22:23], v[22:23], v[238:239]
	v_pk_mul_f32 v[24:25], v[24:25], v[240:241]
	v_pk_mul_f32 v[26:27], v[26:27], v[238:239]
	v_pk_mul_f32 v[28:29], v[28:29], v[240:241]
	v_pk_mul_f32 v[30:31], v[30:31], v[238:239]
	v_pk_mul_f32 v[32:33], v[32:33], v[240:241]
	v_pk_mul_f32 v[34:35], v[34:35], v[238:239]
	v_pk_mul_f32 v[36:37], v[36:37], v[240:241]
	v_pk_mul_f32 v[38:39], v[38:39], v[238:239]
	v_pk_mul_f32 v[40:41], v[40:41], v[240:241]
	v_pk_mul_f32 v[42:43], v[42:43], v[238:239]
	v_pk_mul_f32 v[44:45], v[44:45], v[240:241]
	v_pk_mul_f32 v[46:47], v[46:47], v[238:239]
	v_pk_mul_f32 v[48:49], v[48:49], v[240:241]
	v_pk_mul_f32 v[50:51], v[50:51], v[238:239]
	v_pk_mul_f32 v[52:53], v[52:53], v[240:241]
	v_pk_mul_f32 v[54:55], v[54:55], v[238:239]
	v_pk_mul_f32 v[56:57], v[56:57], v[240:241]
	v_pk_mul_f32 v[58:59], v[58:59], v[238:239]
	v_pk_mul_f32 v[60:61], v[60:61], v[240:241]
	v_pk_mul_f32 v[62:63], v[62:63], v[238:239]
	v_pk_mul_f32 v[64:65], v[64:65], v[240:241]
	v_pk_mul_f32 v[66:67], v[66:67], v[242:243]
	v_pk_mul_f32 v[68:69], v[68:69], v[244:245]
	v_pk_mul_f32 v[70:71], v[70:71], v[242:243]
	v_pk_mul_f32 v[72:73], v[72:73], v[244:245]
	v_pk_mul_f32 v[74:75], v[74:75], v[242:243]
	v_pk_mul_f32 v[76:77], v[76:77], v[244:245]
	v_pk_mul_f32 v[78:79], v[78:79], v[242:243]
	v_pk_mul_f32 v[80:81], v[80:81], v[244:245]
	v_pk_mul_f32 v[82:83], v[82:83], v[242:243]
	v_pk_mul_f32 v[84:85], v[84:85], v[244:245]
	v_pk_mul_f32 v[86:87], v[86:87], v[242:243]
	v_pk_mul_f32 v[88:89], v[88:89], v[244:245]
	v_pk_mul_f32 v[90:91], v[90:91], v[242:243]
	v_pk_mul_f32 v[92:93], v[92:93], v[244:245]
	v_pk_mul_f32 v[94:95], v[94:95], v[242:243]
	v_pk_mul_f32 v[96:97], v[96:97], v[244:245]
	v_pk_mul_f32 v[98:99], v[98:99], v[242:243]
	v_pk_mul_f32 v[100:101], v[100:101], v[244:245]
	v_pk_mul_f32 v[102:103], v[102:103], v[242:243]
	v_pk_mul_f32 v[104:105], v[104:105], v[244:245]
	v_pk_mul_f32 v[106:107], v[106:107], v[242:243]
	v_pk_mul_f32 v[108:109], v[108:109], v[244:245]
	v_pk_mul_f32 v[110:111], v[110:111], v[242:243]
	v_pk_mul_f32 v[112:113], v[112:113], v[244:245]
	v_pk_mul_f32 v[114:115], v[114:115], v[242:243]
	v_pk_mul_f32 v[116:117], v[116:117], v[244:245]
	v_pk_mul_f32 v[118:119], v[118:119], v[242:243]
	v_pk_mul_f32 v[120:121], v[120:121], v[244:245]
	v_pk_mul_f32 v[122:123], v[122:123], v[242:243]
	v_pk_mul_f32 v[124:125], v[124:125], v[244:245]
	v_pk_mul_f32 v[126:127], v[126:127], v[242:243]
	v_pk_mul_f32 v[128:129], v[128:129], v[244:245]
	s_branch .Ld16a_fj0

.LBB0_803:
	v_mov_b32_e32 v246, v0
	v_mov_b32_e32 v247, v223
	s_nop 1
	v_permlane16_swap_b32_e32 v0, v246
	v_permlane16_swap_b32_e32 v223, v247
	v_add_f32_e32 v0, v0, v246
	v_add_f32_e32 v223, v223, v247
	v_mov_b32_e32 v246, v0
	v_mov_b32_e32 v247, v223
	s_nop 1
	v_permlane32_swap_b32_e32 v0, v246
	v_permlane32_swap_b32_e32 v223, v247
	v_add_f32_e32 v0, v0, v246
	v_add_f32_e32 v223, v223, v247
	s_nop 1
	s_and_saveexec_b64 s[34:35], s[0:1]
	ds_write_b32 v232, v0
	ds_write_b32 v232, v223 offset:64
	s_or_b64 exec, exec, s[34:35]
	s_waitcnt lgkmcnt(0)
	ds_read_b128 v[146:149], v231
	ds_read_b128 v[150:153], v231 offset:64
	s_lshl_b64 s[2:3], s[2:3], 12
	s_add_u32 s2, s42, s2
	s_addc_u32 s3, s43, s3
	s_lshl_b32 s4, s52, 9
	s_add_u32 s4, s2, s4
	s_addc_u32 s34, s3, 0
	s_lshl_b64 s[2:3], s[30:31], 12
	s_add_u32 s30, s4, s2
	s_addc_u32 s31, s34, s3
	v_mbcnt_lo_u32_b32 v202, -1, 0
	v_mbcnt_hi_u32_b32 v202, -1, v202
	v_and_b32_e32 v203, 15, v202
	v_lshrrev_b32_e32 v204, 4, v202
	v_lshlrev_b32_e32 v204, 14, v204
	v_lshl_or_b32 v204, v203, 1, v204
	v_and_b32_e32 v203, 1, v202
	v_cmp_eq_u32_e64 s[76:77], 0, v203
	s_waitcnt lgkmcnt(0)
	v_rcp_f32_e32 v146, v146
	v_rcp_f32_e32 v147, v147
	v_rcp_f32_e32 v148, v148
	v_rcp_f32_e32 v149, v149
	v_rcp_f32_e32 v150, v150
	v_rcp_f32_e32 v151, v151
	v_rcp_f32_e32 v152, v152
	v_rcp_f32_e32 v153, v153
	s_nop 0
	v_mov_b32_e32 v205, v204
	v_mul_f32_e32 v2, v2, v146
	v_mul_f32_e32 v6, v6, v146
	v_mul_f32_e32 v10, v10, v146
	v_mul_f32_e32 v14, v14, v146
	v_mul_f32_e32 v18, v18, v146
	v_mul_f32_e32 v22, v22, v146
	v_mul_f32_e32 v26, v26, v146
	v_mul_f32_e32 v30, v30, v146
	v_mul_f32_e32 v34, v34, v146
	v_mul_f32_e32 v38, v38, v146
	v_mul_f32_e32 v42, v42, v146
	v_mul_f32_e32 v46, v46, v146
	v_mul_f32_e32 v50, v50, v146
	v_mul_f32_e32 v54, v54, v146
	v_mul_f32_e32 v58, v58, v146
	v_mul_f32_e32 v62, v62, v146
	v_mov_b32_dpp v162, v2 quad_perm:[1,0,3,2] row_mask:0xf bank_mask:0xf
	v_mov_b32_dpp v163, v6 quad_perm:[1,0,3,2] row_mask:0xf bank_mask:0xf
	v_mov_b32_dpp v164, v10 quad_perm:[1,0,3,2] row_mask:0xf bank_mask:0xf
	v_mov_b32_dpp v165, v14 quad_perm:[1,0,3,2] row_mask:0xf bank_mask:0xf
	v_mov_b32_dpp v166, v18 quad_perm:[1,0,3,2] row_mask:0xf bank_mask:0xf
	v_mov_b32_dpp v167, v22 quad_perm:[1,0,3,2] row_mask:0xf bank_mask:0xf
	v_mov_b32_dpp v168, v26 quad_perm:[1,0,3,2] row_mask:0xf bank_mask:0xf
	v_mov_b32_dpp v169, v30 quad_perm:[1,0,3,2] row_mask:0xf bank_mask:0xf
	v_mov_b32_dpp v170, v34 quad_perm:[1,0,3,2] row_mask:0xf bank_mask:0xf
	v_mov_b32_dpp v171, v38 quad_perm:[1,0,3,2] row_mask:0xf bank_mask:0xf
	v_mov_b32_dpp v172, v42 quad_perm:[1,0,3,2] row_mask:0xf bank_mask:0xf
	v_mov_b32_dpp v173, v46 quad_perm:[1,0,3,2] row_mask:0xf bank_mask:0xf
	v_mov_b32_dpp v174, v50 quad_perm:[1,0,3,2] row_mask:0xf bank_mask:0xf
	v_mov_b32_dpp v175, v54 quad_perm:[1,0,3,2] row_mask:0xf bank_mask:0xf
	v_mov_b32_dpp v176, v58 quad_perm:[1,0,3,2] row_mask:0xf bank_mask:0xf
	v_mov_b32_dpp v177, v62 quad_perm:[1,0,3,2] row_mask:0xf bank_mask:0xf
	v_cvt_pk_bf16_f32 v2, v2, v162
	v_cvt_pk_bf16_f32 v6, v6, v163
	v_cvt_pk_bf16_f32 v10, v10, v164
	v_cvt_pk_bf16_f32 v14, v14, v165
	v_cvt_pk_bf16_f32 v18, v18, v166
	v_cvt_pk_bf16_f32 v22, v22, v167
	v_cvt_pk_bf16_f32 v26, v26, v168
	v_cvt_pk_bf16_f32 v30, v30, v169
	v_cvt_pk_bf16_f32 v34, v34, v170
	v_cvt_pk_bf16_f32 v38, v38, v171
	v_cvt_pk_bf16_f32 v42, v42, v172
	v_cvt_pk_bf16_f32 v46, v46, v173
	v_cvt_pk_bf16_f32 v50, v50, v174
	v_cvt_pk_bf16_f32 v54, v54, v175
	v_cvt_pk_bf16_f32 v58, v58, v176
	v_cvt_pk_bf16_f32 v62, v62, v177
	s_mov_b64 exec, s[76:77]
	global_store_dword v205, v2, s[30:31] offset:0
	global_store_dword v205, v6, s[30:31] offset:32
	global_store_dword v205, v10, s[30:31] offset:64
	global_store_dword v205, v14, s[30:31] offset:96
	global_store_dword v205, v18, s[30:31] offset:128
	global_store_dword v205, v22, s[30:31] offset:160
	global_store_dword v205, v26, s[30:31] offset:192
	global_store_dword v205, v30, s[30:31] offset:224
	global_store_dword v205, v34, s[30:31] offset:256
	global_store_dword v205, v38, s[30:31] offset:288
	global_store_dword v205, v42, s[30:31] offset:320
	global_store_dword v205, v46, s[30:31] offset:352
	global_store_dword v205, v50, s[30:31] offset:384
	global_store_dword v205, v54, s[30:31] offset:416
	global_store_dword v205, v58, s[30:31] offset:448
	global_store_dword v205, v62, s[30:31] offset:480
	s_mov_b64 exec, -1
	v_add_u32_e32 v205, 0x1000, v204
	v_mul_f32_e32 v3, v3, v147
	v_mul_f32_e32 v7, v7, v147
	v_mul_f32_e32 v11, v11, v147
	v_mul_f32_e32 v15, v15, v147
	v_mul_f32_e32 v19, v19, v147
	v_mul_f32_e32 v23, v23, v147
	v_mul_f32_e32 v27, v27, v147
	v_mul_f32_e32 v31, v31, v147
	v_mul_f32_e32 v35, v35, v147
	v_mul_f32_e32 v39, v39, v147
	v_mul_f32_e32 v43, v43, v147
	v_mul_f32_e32 v47, v47, v147
	v_mul_f32_e32 v51, v51, v147
	v_mul_f32_e32 v55, v55, v147
	v_mul_f32_e32 v59, v59, v147
	v_mul_f32_e32 v63, v63, v147
	v_mov_b32_dpp v162, v3 quad_perm:[1,0,3,2] row_mask:0xf bank_mask:0xf
	v_mov_b32_dpp v163, v7 quad_perm:[1,0,3,2] row_mask:0xf bank_mask:0xf
	v_mov_b32_dpp v164, v11 quad_perm:[1,0,3,2] row_mask:0xf bank_mask:0xf
	v_mov_b32_dpp v165, v15 quad_perm:[1,0,3,2] row_mask:0xf bank_mask:0xf
	v_mov_b32_dpp v166, v19 quad_perm:[1,0,3,2] row_mask:0xf bank_mask:0xf
	v_mov_b32_dpp v167, v23 quad_perm:[1,0,3,2] row_mask:0xf bank_mask:0xf
	v_mov_b32_dpp v168, v27 quad_perm:[1,0,3,2] row_mask:0xf bank_mask:0xf
	v_mov_b32_dpp v169, v31 quad_perm:[1,0,3,2] row_mask:0xf bank_mask:0xf
	v_mov_b32_dpp v170, v35 quad_perm:[1,0,3,2] row_mask:0xf bank_mask:0xf
	v_mov_b32_dpp v171, v39 quad_perm:[1,0,3,2] row_mask:0xf bank_mask:0xf
	v_mov_b32_dpp v172, v43 quad_perm:[1,0,3,2] row_mask:0xf bank_mask:0xf
	v_mov_b32_dpp v173, v47 quad_perm:[1,0,3,2] row_mask:0xf bank_mask:0xf
	v_mov_b32_dpp v174, v51 quad_perm:[1,0,3,2] row_mask:0xf bank_mask:0xf
	v_mov_b32_dpp v175, v55 quad_perm:[1,0,3,2] row_mask:0xf bank_mask:0xf
	v_mov_b32_dpp v176, v59 quad_perm:[1,0,3,2] row_mask:0xf bank_mask:0xf
	v_mov_b32_dpp v177, v63 quad_perm:[1,0,3,2] row_mask:0xf bank_mask:0xf
	v_cvt_pk_bf16_f32 v3, v3, v162
	v_cvt_pk_bf16_f32 v7, v7, v163
	v_cvt_pk_bf16_f32 v11, v11, v164
	v_cvt_pk_bf16_f32 v15, v15, v165
	v_cvt_pk_bf16_f32 v19, v19, v166
	v_cvt_pk_bf16_f32 v23, v23, v167
	v_cvt_pk_bf16_f32 v27, v27, v168
	v_cvt_pk_bf16_f32 v31, v31, v169
	v_cvt_pk_bf16_f32 v35, v35, v170
	v_cvt_pk_bf16_f32 v39, v39, v171
	v_cvt_pk_bf16_f32 v43, v43, v172
	v_cvt_pk_bf16_f32 v47, v47, v173
	v_cvt_pk_bf16_f32 v51, v51, v174
	v_cvt_pk_bf16_f32 v55, v55, v175
	v_cvt_pk_bf16_f32 v59, v59, v176
	v_cvt_pk_bf16_f32 v63, v63, v177
	s_mov_b64 exec, s[76:77]
	global_store_dword v205, v3, s[30:31] offset:0
	global_store_dword v205, v7, s[30:31] offset:32
	global_store_dword v205, v11, s[30:31] offset:64
	global_store_dword v205, v15, s[30:31] offset:96
	global_store_dword v205, v19, s[30:31] offset:128
	global_store_dword v205, v23, s[30:31] offset:160
	global_store_dword v205, v27, s[30:31] offset:192
	global_store_dword v205, v31, s[30:31] offset:224
	global_store_dword v205, v35, s[30:31] offset:256
	global_store_dword v205, v39, s[30:31] offset:288
	global_store_dword v205, v43, s[30:31] offset:320
	global_store_dword v205, v47, s[30:31] offset:352
	global_store_dword v205, v51, s[30:31] offset:384
	global_store_dword v205, v55, s[30:31] offset:416
	global_store_dword v205, v59, s[30:31] offset:448
	global_store_dword v205, v63, s[30:31] offset:480
	s_mov_b64 exec, -1
	v_add_u32_e32 v205, 0x2000, v204
	v_mul_f32_e32 v4, v4, v148
	v_mul_f32_e32 v8, v8, v148
	v_mul_f32_e32 v12, v12, v148
	v_mul_f32_e32 v16, v16, v148
	v_mul_f32_e32 v20, v20, v148
	v_mul_f32_e32 v24, v24, v148
	v_mul_f32_e32 v28, v28, v148
	v_mul_f32_e32 v32, v32, v148
	v_mul_f32_e32 v36, v36, v148
	v_mul_f32_e32 v40, v40, v148
	v_mul_f32_e32 v44, v44, v148
	v_mul_f32_e32 v48, v48, v148
	v_mul_f32_e32 v52, v52, v148
	v_mul_f32_e32 v56, v56, v148
	v_mul_f32_e32 v60, v60, v148
	v_mul_f32_e32 v64, v64, v148
	v_mov_b32_dpp v162, v4 quad_perm:[1,0,3,2] row_mask:0xf bank_mask:0xf
	v_mov_b32_dpp v163, v8 quad_perm:[1,0,3,2] row_mask:0xf bank_mask:0xf
	v_mov_b32_dpp v164, v12 quad_perm:[1,0,3,2] row_mask:0xf bank_mask:0xf
	v_mov_b32_dpp v165, v16 quad_perm:[1,0,3,2] row_mask:0xf bank_mask:0xf
	v_mov_b32_dpp v166, v20 quad_perm:[1,0,3,2] row_mask:0xf bank_mask:0xf
	v_mov_b32_dpp v167, v24 quad_perm:[1,0,3,2] row_mask:0xf bank_mask:0xf
	v_mov_b32_dpp v168, v28 quad_perm:[1,0,3,2] row_mask:0xf bank_mask:0xf
	v_mov_b32_dpp v169, v32 quad_perm:[1,0,3,2] row_mask:0xf bank_mask:0xf
	v_mov_b32_dpp v170, v36 quad_perm:[1,0,3,2] row_mask:0xf bank_mask:0xf
	v_mov_b32_dpp v171, v40 quad_perm:[1,0,3,2] row_mask:0xf bank_mask:0xf
	v_mov_b32_dpp v172, v44 quad_perm:[1,0,3,2] row_mask:0xf bank_mask:0xf
	v_mov_b32_dpp v173, v48 quad_perm:[1,0,3,2] row_mask:0xf bank_mask:0xf
	v_mov_b32_dpp v174, v52 quad_perm:[1,0,3,2] row_mask:0xf bank_mask:0xf
	v_mov_b32_dpp v175, v56 quad_perm:[1,0,3,2] row_mask:0xf bank_mask:0xf
	v_mov_b32_dpp v176, v60 quad_perm:[1,0,3,2] row_mask:0xf bank_mask:0xf
	v_mov_b32_dpp v177, v64 quad_perm:[1,0,3,2] row_mask:0xf bank_mask:0xf
	v_cvt_pk_bf16_f32 v4, v4, v162
	v_cvt_pk_bf16_f32 v8, v8, v163
	v_cvt_pk_bf16_f32 v12, v12, v164
	v_cvt_pk_bf16_f32 v16, v16, v165
	v_cvt_pk_bf16_f32 v20, v20, v166
	v_cvt_pk_bf16_f32 v24, v24, v167
	v_cvt_pk_bf16_f32 v28, v28, v168
	v_cvt_pk_bf16_f32 v32, v32, v169
	v_cvt_pk_bf16_f32 v36, v36, v170
	v_cvt_pk_bf16_f32 v40, v40, v171
	v_cvt_pk_bf16_f32 v44, v44, v172
	v_cvt_pk_bf16_f32 v48, v48, v173
	v_cvt_pk_bf16_f32 v52, v52, v174
	v_cvt_pk_bf16_f32 v56, v56, v175
	v_cvt_pk_bf16_f32 v60, v60, v176
	v_cvt_pk_bf16_f32 v64, v64, v177
	s_mov_b64 exec, s[76:77]
	global_store_dword v205, v4, s[30:31] offset:0
	global_store_dword v205, v8, s[30:31] offset:32
	global_store_dword v205, v12, s[30:31] offset:64
	global_store_dword v205, v16, s[30:31] offset:96
	global_store_dword v205, v20, s[30:31] offset:128
	global_store_dword v205, v24, s[30:31] offset:160
	global_store_dword v205, v28, s[30:31] offset:192
	global_store_dword v205, v32, s[30:31] offset:224
	global_store_dword v205, v36, s[30:31] offset:256
	global_store_dword v205, v40, s[30:31] offset:288
	global_store_dword v205, v44, s[30:31] offset:320
	global_store_dword v205, v48, s[30:31] offset:352
	global_store_dword v205, v52, s[30:31] offset:384
	global_store_dword v205, v56, s[30:31] offset:416
	global_store_dword v205, v60, s[30:31] offset:448
	global_store_dword v205, v64, s[30:31] offset:480
	s_mov_b64 exec, -1
	v_add_u32_e32 v205, 0x3000, v204
	v_mul_f32_e32 v5, v5, v149
	v_mul_f32_e32 v9, v9, v149
	v_mul_f32_e32 v13, v13, v149
	v_mul_f32_e32 v17, v17, v149
	v_mul_f32_e32 v21, v21, v149
	v_mul_f32_e32 v25, v25, v149
	v_mul_f32_e32 v29, v29, v149
	v_mul_f32_e32 v33, v33, v149
	v_mul_f32_e32 v37, v37, v149
	v_mul_f32_e32 v41, v41, v149
	v_mul_f32_e32 v45, v45, v149
	v_mul_f32_e32 v49, v49, v149
	v_mul_f32_e32 v53, v53, v149
	v_mul_f32_e32 v57, v57, v149
	v_mul_f32_e32 v61, v61, v149
	v_mul_f32_e32 v65, v65, v149
	v_mov_b32_dpp v162, v5 quad_perm:[1,0,3,2] row_mask:0xf bank_mask:0xf
	v_mov_b32_dpp v163, v9 quad_perm:[1,0,3,2] row_mask:0xf bank_mask:0xf
	v_mov_b32_dpp v164, v13 quad_perm:[1,0,3,2] row_mask:0xf bank_mask:0xf
	v_mov_b32_dpp v165, v17 quad_perm:[1,0,3,2] row_mask:0xf bank_mask:0xf
	v_mov_b32_dpp v166, v21 quad_perm:[1,0,3,2] row_mask:0xf bank_mask:0xf
	v_mov_b32_dpp v167, v25 quad_perm:[1,0,3,2] row_mask:0xf bank_mask:0xf
	v_mov_b32_dpp v168, v29 quad_perm:[1,0,3,2] row_mask:0xf bank_mask:0xf
	v_mov_b32_dpp v169, v33 quad_perm:[1,0,3,2] row_mask:0xf bank_mask:0xf
	v_mov_b32_dpp v170, v37 quad_perm:[1,0,3,2] row_mask:0xf bank_mask:0xf
	v_mov_b32_dpp v171, v41 quad_perm:[1,0,3,2] row_mask:0xf bank_mask:0xf
	v_mov_b32_dpp v172, v45 quad_perm:[1,0,3,2] row_mask:0xf bank_mask:0xf
	v_mov_b32_dpp v173, v49 quad_perm:[1,0,3,2] row_mask:0xf bank_mask:0xf
	v_mov_b32_dpp v174, v53 quad_perm:[1,0,3,2] row_mask:0xf bank_mask:0xf
	v_mov_b32_dpp v175, v57 quad_perm:[1,0,3,2] row_mask:0xf bank_mask:0xf
	v_mov_b32_dpp v176, v61 quad_perm:[1,0,3,2] row_mask:0xf bank_mask:0xf
	v_mov_b32_dpp v177, v65 quad_perm:[1,0,3,2] row_mask:0xf bank_mask:0xf
	v_cvt_pk_bf16_f32 v5, v5, v162
	v_cvt_pk_bf16_f32 v9, v9, v163
	v_cvt_pk_bf16_f32 v13, v13, v164
	v_cvt_pk_bf16_f32 v17, v17, v165
	v_cvt_pk_bf16_f32 v21, v21, v166
	v_cvt_pk_bf16_f32 v25, v25, v167
	v_cvt_pk_bf16_f32 v29, v29, v168
	v_cvt_pk_bf16_f32 v33, v33, v169
	v_cvt_pk_bf16_f32 v37, v37, v170
	v_cvt_pk_bf16_f32 v41, v41, v171
	v_cvt_pk_bf16_f32 v45, v45, v172
	v_cvt_pk_bf16_f32 v49, v49, v173
	v_cvt_pk_bf16_f32 v53, v53, v174
	v_cvt_pk_bf16_f32 v57, v57, v175
	v_cvt_pk_bf16_f32 v61, v61, v176
	v_cvt_pk_bf16_f32 v65, v65, v177
	s_mov_b64 exec, s[76:77]
	global_store_dword v205, v5, s[30:31] offset:0
	global_store_dword v205, v9, s[30:31] offset:32
	global_store_dword v205, v13, s[30:31] offset:64
	global_store_dword v205, v17, s[30:31] offset:96
	global_store_dword v205, v21, s[30:31] offset:128
	global_store_dword v205, v25, s[30:31] offset:160
	global_store_dword v205, v29, s[30:31] offset:192
	global_store_dword v205, v33, s[30:31] offset:224
	global_store_dword v205, v37, s[30:31] offset:256
	global_store_dword v205, v41, s[30:31] offset:288
	global_store_dword v205, v45, s[30:31] offset:320
	global_store_dword v205, v49, s[30:31] offset:352
	global_store_dword v205, v53, s[30:31] offset:384
	global_store_dword v205, v57, s[30:31] offset:416
	global_store_dword v205, v61, s[30:31] offset:448
	global_store_dword v205, v65, s[30:31] offset:480
	s_mov_b64 exec, -1
	v_add_u32_e32 v205, 0x10000, v204
	v_mul_f32_e32 v66, v66, v150
	v_mul_f32_e32 v70, v70, v150
	v_mul_f32_e32 v74, v74, v150
	v_mul_f32_e32 v78, v78, v150
	v_mul_f32_e32 v82, v82, v150
	v_mul_f32_e32 v86, v86, v150
	v_mul_f32_e32 v90, v90, v150
	v_mul_f32_e32 v94, v94, v150
	v_mul_f32_e32 v98, v98, v150
	v_mul_f32_e32 v102, v102, v150
	v_mul_f32_e32 v106, v106, v150
	v_mul_f32_e32 v110, v110, v150
	v_mul_f32_e32 v114, v114, v150
	v_mul_f32_e32 v118, v118, v150
	v_mul_f32_e32 v122, v122, v150
	v_mul_f32_e32 v126, v126, v150
	v_mov_b32_dpp v162, v66 quad_perm:[1,0,3,2] row_mask:0xf bank_mask:0xf
	v_mov_b32_dpp v163, v70 quad_perm:[1,0,3,2] row_mask:0xf bank_mask:0xf
	v_mov_b32_dpp v164, v74 quad_perm:[1,0,3,2] row_mask:0xf bank_mask:0xf
	v_mov_b32_dpp v165, v78 quad_perm:[1,0,3,2] row_mask:0xf bank_mask:0xf
	v_mov_b32_dpp v166, v82 quad_perm:[1,0,3,2] row_mask:0xf bank_mask:0xf
	v_mov_b32_dpp v167, v86 quad_perm:[1,0,3,2] row_mask:0xf bank_mask:0xf
	v_mov_b32_dpp v168, v90 quad_perm:[1,0,3,2] row_mask:0xf bank_mask:0xf
	v_mov_b32_dpp v169, v94 quad_perm:[1,0,3,2] row_mask:0xf bank_mask:0xf
	v_mov_b32_dpp v170, v98 quad_perm:[1,0,3,2] row_mask:0xf bank_mask:0xf
	v_mov_b32_dpp v171, v102 quad_perm:[1,0,3,2] row_mask:0xf bank_mask:0xf
	v_mov_b32_dpp v172, v106 quad_perm:[1,0,3,2] row_mask:0xf bank_mask:0xf
	v_mov_b32_dpp v173, v110 quad_perm:[1,0,3,2] row_mask:0xf bank_mask:0xf
	v_mov_b32_dpp v174, v114 quad_perm:[1,0,3,2] row_mask:0xf bank_mask:0xf
	v_mov_b32_dpp v175, v118 quad_perm:[1,0,3,2] row_mask:0xf bank_mask:0xf
	v_mov_b32_dpp v176, v122 quad_perm:[1,0,3,2] row_mask:0xf bank_mask:0xf
	v_mov_b32_dpp v177, v126 quad_perm:[1,0,3,2] row_mask:0xf bank_mask:0xf
	v_cvt_pk_bf16_f32 v66, v66, v162
	v_cvt_pk_bf16_f32 v70, v70, v163
	v_cvt_pk_bf16_f32 v74, v74, v164
	v_cvt_pk_bf16_f32 v78, v78, v165
	v_cvt_pk_bf16_f32 v82, v82, v166
	v_cvt_pk_bf16_f32 v86, v86, v167
	v_cvt_pk_bf16_f32 v90, v90, v168
	v_cvt_pk_bf16_f32 v94, v94, v169
	v_cvt_pk_bf16_f32 v98, v98, v170
	v_cvt_pk_bf16_f32 v102, v102, v171
	v_cvt_pk_bf16_f32 v106, v106, v172
	v_cvt_pk_bf16_f32 v110, v110, v173
	v_cvt_pk_bf16_f32 v114, v114, v174
	v_cvt_pk_bf16_f32 v118, v118, v175
	v_cvt_pk_bf16_f32 v122, v122, v176
	v_cvt_pk_bf16_f32 v126, v126, v177
	s_mov_b64 exec, s[76:77]
	global_store_dword v205, v66, s[30:31] offset:0
	global_store_dword v205, v70, s[30:31] offset:32
	global_store_dword v205, v74, s[30:31] offset:64
	global_store_dword v205, v78, s[30:31] offset:96
	global_store_dword v205, v82, s[30:31] offset:128
	global_store_dword v205, v86, s[30:31] offset:160
	global_store_dword v205, v90, s[30:31] offset:192
	global_store_dword v205, v94, s[30:31] offset:224
	global_store_dword v205, v98, s[30:31] offset:256
	global_store_dword v205, v102, s[30:31] offset:288
	global_store_dword v205, v106, s[30:31] offset:320
	global_store_dword v205, v110, s[30:31] offset:352
	global_store_dword v205, v114, s[30:31] offset:384
	global_store_dword v205, v118, s[30:31] offset:416
	global_store_dword v205, v122, s[30:31] offset:448
	global_store_dword v205, v126, s[30:31] offset:480
	s_mov_b64 exec, -1
	v_add_u32_e32 v205, 0x11000, v204
	v_mul_f32_e32 v67, v67, v151
	v_mul_f32_e32 v71, v71, v151
	v_mul_f32_e32 v75, v75, v151
	v_mul_f32_e32 v79, v79, v151
	v_mul_f32_e32 v83, v83, v151
	v_mul_f32_e32 v87, v87, v151
	v_mul_f32_e32 v91, v91, v151
	v_mul_f32_e32 v95, v95, v151
	v_mul_f32_e32 v99, v99, v151
	v_mul_f32_e32 v103, v103, v151
	v_mul_f32_e32 v107, v107, v151
	v_mul_f32_e32 v111, v111, v151
	v_mul_f32_e32 v115, v115, v151
	v_mul_f32_e32 v119, v119, v151
	v_mul_f32_e32 v123, v123, v151
	v_mul_f32_e32 v127, v127, v151
	v_mov_b32_dpp v162, v67 quad_perm:[1,0,3,2] row_mask:0xf bank_mask:0xf
	v_mov_b32_dpp v163, v71 quad_perm:[1,0,3,2] row_mask:0xf bank_mask:0xf
	v_mov_b32_dpp v164, v75 quad_perm:[1,0,3,2] row_mask:0xf bank_mask:0xf
	v_mov_b32_dpp v165, v79 quad_perm:[1,0,3,2] row_mask:0xf bank_mask:0xf
	v_mov_b32_dpp v166, v83 quad_perm:[1,0,3,2] row_mask:0xf bank_mask:0xf
	v_mov_b32_dpp v167, v87 quad_perm:[1,0,3,2] row_mask:0xf bank_mask:0xf
	v_mov_b32_dpp v168, v91 quad_perm:[1,0,3,2] row_mask:0xf bank_mask:0xf
	v_mov_b32_dpp v169, v95 quad_perm:[1,0,3,2] row_mask:0xf bank_mask:0xf
	v_mov_b32_dpp v170, v99 quad_perm:[1,0,3,2] row_mask:0xf bank_mask:0xf
	v_mov_b32_dpp v171, v103 quad_perm:[1,0,3,2] row_mask:0xf bank_mask:0xf
	v_mov_b32_dpp v172, v107 quad_perm:[1,0,3,2] row_mask:0xf bank_mask:0xf
	v_mov_b32_dpp v173, v111 quad_perm:[1,0,3,2] row_mask:0xf bank_mask:0xf
	v_mov_b32_dpp v174, v115 quad_perm:[1,0,3,2] row_mask:0xf bank_mask:0xf
	v_mov_b32_dpp v175, v119 quad_perm:[1,0,3,2] row_mask:0xf bank_mask:0xf
	v_mov_b32_dpp v176, v123 quad_perm:[1,0,3,2] row_mask:0xf bank_mask:0xf
	v_mov_b32_dpp v177, v127 quad_perm:[1,0,3,2] row_mask:0xf bank_mask:0xf
	v_cvt_pk_bf16_f32 v67, v67, v162
	v_cvt_pk_bf16_f32 v71, v71, v163
	v_cvt_pk_bf16_f32 v75, v75, v164
	v_cvt_pk_bf16_f32 v79, v79, v165
	v_cvt_pk_bf16_f32 v83, v83, v166
	v_cvt_pk_bf16_f32 v87, v87, v167
	v_cvt_pk_bf16_f32 v91, v91, v168
	v_cvt_pk_bf16_f32 v95, v95, v169
	v_cvt_pk_bf16_f32 v99, v99, v170
	v_cvt_pk_bf16_f32 v103, v103, v171
	v_cvt_pk_bf16_f32 v107, v107, v172
	v_cvt_pk_bf16_f32 v111, v111, v173
	v_cvt_pk_bf16_f32 v115, v115, v174
	v_cvt_pk_bf16_f32 v119, v119, v175
	v_cvt_pk_bf16_f32 v123, v123, v176
	v_cvt_pk_bf16_f32 v127, v127, v177
	s_mov_b64 exec, s[76:77]
	global_store_dword v205, v67, s[30:31] offset:0
	global_store_dword v205, v71, s[30:31] offset:32
	global_store_dword v205, v75, s[30:31] offset:64
	global_store_dword v205, v79, s[30:31] offset:96
	global_store_dword v205, v83, s[30:31] offset:128
	global_store_dword v205, v87, s[30:31] offset:160
	global_store_dword v205, v91, s[30:31] offset:192
	global_store_dword v205, v95, s[30:31] offset:224
	global_store_dword v205, v99, s[30:31] offset:256
	global_store_dword v205, v103, s[30:31] offset:288
	global_store_dword v205, v107, s[30:31] offset:320
	global_store_dword v205, v111, s[30:31] offset:352
	global_store_dword v205, v115, s[30:31] offset:384
	global_store_dword v205, v119, s[30:31] offset:416
	global_store_dword v205, v123, s[30:31] offset:448
	global_store_dword v205, v127, s[30:31] offset:480
	s_mov_b64 exec, -1
	v_add_u32_e32 v205, 0x12000, v204
	v_mul_f32_e32 v68, v68, v152
	v_mul_f32_e32 v72, v72, v152
	v_mul_f32_e32 v76, v76, v152
	v_mul_f32_e32 v80, v80, v152
	v_mul_f32_e32 v84, v84, v152
	v_mul_f32_e32 v88, v88, v152
	v_mul_f32_e32 v92, v92, v152
	v_mul_f32_e32 v96, v96, v152
	v_mul_f32_e32 v100, v100, v152
	v_mul_f32_e32 v104, v104, v152
	v_mul_f32_e32 v108, v108, v152
	v_mul_f32_e32 v112, v112, v152
	v_mul_f32_e32 v116, v116, v152
	v_mul_f32_e32 v120, v120, v152
	v_mul_f32_e32 v124, v124, v152
	v_mul_f32_e32 v128, v128, v152
	v_mov_b32_dpp v162, v68 quad_perm:[1,0,3,2] row_mask:0xf bank_mask:0xf
	v_mov_b32_dpp v163, v72 quad_perm:[1,0,3,2] row_mask:0xf bank_mask:0xf
	v_mov_b32_dpp v164, v76 quad_perm:[1,0,3,2] row_mask:0xf bank_mask:0xf
	v_mov_b32_dpp v165, v80 quad_perm:[1,0,3,2] row_mask:0xf bank_mask:0xf
	v_mov_b32_dpp v166, v84 quad_perm:[1,0,3,2] row_mask:0xf bank_mask:0xf
	v_mov_b32_dpp v167, v88 quad_perm:[1,0,3,2] row_mask:0xf bank_mask:0xf
	v_mov_b32_dpp v168, v92 quad_perm:[1,0,3,2] row_mask:0xf bank_mask:0xf
	v_mov_b32_dpp v169, v96 quad_perm:[1,0,3,2] row_mask:0xf bank_mask:0xf
	v_mov_b32_dpp v170, v100 quad_perm:[1,0,3,2] row_mask:0xf bank_mask:0xf
	v_mov_b32_dpp v171, v104 quad_perm:[1,0,3,2] row_mask:0xf bank_mask:0xf
	v_mov_b32_dpp v172, v108 quad_perm:[1,0,3,2] row_mask:0xf bank_mask:0xf
	v_mov_b32_dpp v173, v112 quad_perm:[1,0,3,2] row_mask:0xf bank_mask:0xf
	v_mov_b32_dpp v174, v116 quad_perm:[1,0,3,2] row_mask:0xf bank_mask:0xf
	v_mov_b32_dpp v175, v120 quad_perm:[1,0,3,2] row_mask:0xf bank_mask:0xf
	v_mov_b32_dpp v176, v124 quad_perm:[1,0,3,2] row_mask:0xf bank_mask:0xf
	v_mov_b32_dpp v177, v128 quad_perm:[1,0,3,2] row_mask:0xf bank_mask:0xf
	v_cvt_pk_bf16_f32 v68, v68, v162
	v_cvt_pk_bf16_f32 v72, v72, v163
	v_cvt_pk_bf16_f32 v76, v76, v164
	v_cvt_pk_bf16_f32 v80, v80, v165
	v_cvt_pk_bf16_f32 v84, v84, v166
	v_cvt_pk_bf16_f32 v88, v88, v167
	v_cvt_pk_bf16_f32 v92, v92, v168
	v_cvt_pk_bf16_f32 v96, v96, v169
	v_cvt_pk_bf16_f32 v100, v100, v170
	v_cvt_pk_bf16_f32 v104, v104, v171
	v_cvt_pk_bf16_f32 v108, v108, v172
	v_cvt_pk_bf16_f32 v112, v112, v173
	v_cvt_pk_bf16_f32 v116, v116, v174
	v_cvt_pk_bf16_f32 v120, v120, v175
	v_cvt_pk_bf16_f32 v124, v124, v176
	v_cvt_pk_bf16_f32 v128, v128, v177
	s_mov_b64 exec, s[76:77]
	global_store_dword v205, v68, s[30:31] offset:0
	global_store_dword v205, v72, s[30:31] offset:32
	global_store_dword v205, v76, s[30:31] offset:64
	global_store_dword v205, v80, s[30:31] offset:96
	global_store_dword v205, v84, s[30:31] offset:128
	global_store_dword v205, v88, s[30:31] offset:160
	global_store_dword v205, v92, s[30:31] offset:192
	global_store_dword v205, v96, s[30:31] offset:224
	global_store_dword v205, v100, s[30:31] offset:256
	global_store_dword v205, v104, s[30:31] offset:288
	global_store_dword v205, v108, s[30:31] offset:320
	global_store_dword v205, v112, s[30:31] offset:352
	global_store_dword v205, v116, s[30:31] offset:384
	global_store_dword v205, v120, s[30:31] offset:416
	global_store_dword v205, v124, s[30:31] offset:448
	global_store_dword v205, v128, s[30:31] offset:480
	s_mov_b64 exec, -1
	v_add_u32_e32 v205, 0x13000, v204
	v_mul_f32_e32 v69, v69, v153
	v_mul_f32_e32 v73, v73, v153
	v_mul_f32_e32 v77, v77, v153
	v_mul_f32_e32 v81, v81, v153
	v_mul_f32_e32 v85, v85, v153
	v_mul_f32_e32 v89, v89, v153
	v_mul_f32_e32 v93, v93, v153
	v_mul_f32_e32 v97, v97, v153
	v_mul_f32_e32 v101, v101, v153
	v_mul_f32_e32 v105, v105, v153
	v_mul_f32_e32 v109, v109, v153
	v_mul_f32_e32 v113, v113, v153
	v_mul_f32_e32 v117, v117, v153
	v_mul_f32_e32 v121, v121, v153
	v_mul_f32_e32 v125, v125, v153
	v_mul_f32_e32 v129, v129, v153
	v_mov_b32_dpp v162, v69 quad_perm:[1,0,3,2] row_mask:0xf bank_mask:0xf
	v_mov_b32_dpp v163, v73 quad_perm:[1,0,3,2] row_mask:0xf bank_mask:0xf
	v_mov_b32_dpp v164, v77 quad_perm:[1,0,3,2] row_mask:0xf bank_mask:0xf
	v_mov_b32_dpp v165, v81 quad_perm:[1,0,3,2] row_mask:0xf bank_mask:0xf
	v_mov_b32_dpp v166, v85 quad_perm:[1,0,3,2] row_mask:0xf bank_mask:0xf
	v_mov_b32_dpp v167, v89 quad_perm:[1,0,3,2] row_mask:0xf bank_mask:0xf
	v_mov_b32_dpp v168, v93 quad_perm:[1,0,3,2] row_mask:0xf bank_mask:0xf
	v_mov_b32_dpp v169, v97 quad_perm:[1,0,3,2] row_mask:0xf bank_mask:0xf
	v_mov_b32_dpp v170, v101 quad_perm:[1,0,3,2] row_mask:0xf bank_mask:0xf
	v_mov_b32_dpp v171, v105 quad_perm:[1,0,3,2] row_mask:0xf bank_mask:0xf
	v_mov_b32_dpp v172, v109 quad_perm:[1,0,3,2] row_mask:0xf bank_mask:0xf
	v_mov_b32_dpp v173, v113 quad_perm:[1,0,3,2] row_mask:0xf bank_mask:0xf
	v_mov_b32_dpp v174, v117 quad_perm:[1,0,3,2] row_mask:0xf bank_mask:0xf
	v_mov_b32_dpp v175, v121 quad_perm:[1,0,3,2] row_mask:0xf bank_mask:0xf
	v_mov_b32_dpp v176, v125 quad_perm:[1,0,3,2] row_mask:0xf bank_mask:0xf
	v_mov_b32_dpp v177, v129 quad_perm:[1,0,3,2] row_mask:0xf bank_mask:0xf
	v_cvt_pk_bf16_f32 v69, v69, v162
	v_cvt_pk_bf16_f32 v73, v73, v163
	v_cvt_pk_bf16_f32 v77, v77, v164
	v_cvt_pk_bf16_f32 v81, v81, v165
	v_cvt_pk_bf16_f32 v85, v85, v166
	v_cvt_pk_bf16_f32 v89, v89, v167
	v_cvt_pk_bf16_f32 v93, v93, v168
	v_cvt_pk_bf16_f32 v97, v97, v169
	v_cvt_pk_bf16_f32 v101, v101, v170
	v_cvt_pk_bf16_f32 v105, v105, v171
	v_cvt_pk_bf16_f32 v109, v109, v172
	v_cvt_pk_bf16_f32 v113, v113, v173
	v_cvt_pk_bf16_f32 v117, v117, v174
	v_cvt_pk_bf16_f32 v121, v121, v175
	v_cvt_pk_bf16_f32 v125, v125, v176
	v_cvt_pk_bf16_f32 v129, v129, v177
	s_mov_b64 exec, s[76:77]
	global_store_dword v205, v69, s[30:31] offset:0
	global_store_dword v205, v73, s[30:31] offset:32
	global_store_dword v205, v77, s[30:31] offset:64
	global_store_dword v205, v81, s[30:31] offset:96
	global_store_dword v205, v85, s[30:31] offset:128
	global_store_dword v205, v89, s[30:31] offset:160
	global_store_dword v205, v93, s[30:31] offset:192
	global_store_dword v205, v97, s[30:31] offset:224
	global_store_dword v205, v101, s[30:31] offset:256
	global_store_dword v205, v105, s[30:31] offset:288
	global_store_dword v205, v109, s[30:31] offset:320
	global_store_dword v205, v113, s[30:31] offset:352
	global_store_dword v205, v117, s[30:31] offset:384
	global_store_dword v205, v121, s[30:31] offset:416
	global_store_dword v205, v125, s[30:31] offset:448
	global_store_dword v205, v129, s[30:31] offset:480
	s_mov_b64 exec, -1
	s_mov_b64 s[30:31], -1
	s_branch .LBB0_784

.LBB0_2405:
	s_lshr_b32 s56, s51, 1
	s_lshl_b32 s2, s56, 7
	v_readlane_b32 s3, v251, 38
	s_add_i32 s4, s3, s2
	s_lshl_b64 s[38:39], s[4:5], 1
	s_bitcmp0_b32 s51, 0
	v_readlane_b32 s2, v251, 34
	v_readlane_b32 s3, v251, 36
	s_cselect_b32 s3, s3, s2
	v_readlane_b32 s64, v251, 32
	s_or_b32 s2, s64, s3
	s_mul_hi_u32 s4, s2, 0x3000
	v_readlane_b32 s36, v251, 44
	s_add_i32 s4, s4, s36
	s_mul_i32 s36, s2, 0x3000
	s_add_u32 s36, s48, s36
	s_addc_u32 s4, s49, s4
	s_add_u32 s42, s36, s38
	s_addc_u32 s43, s4, s39
	s_add_u32 s40, s44, s38
	v_readfirstlane_b32 s4, v208
	s_addc_u32 s41, s45, s39
	s_ashr_i32 s60, s4, 6
	s_and_b32 s4, s4, 0x3fffffc0
	s_lshl_b32 s4, s4, 2
	s_lshl_b32 s37, s60, 3
	s_lshl_b32 s36, s60, 5
	s_add_i32 s4, s4, 0
	v_or_b32_e32 v0, s37, v212
	v_bitop3_b32 v7, s37, v229, v214 bitop3:0xc8
	s_lshl_b32 s37, s60, 2
	s_add_i32 s61, s4, 0x18000
	s_add_i32 s4, s36, s3
	s_and_b32 s62, s37, 4
	s_lshl_b32 s57, s60, 11
	s_lshl_b32 s58, s60, 12
	s_ashr_i32 s37, s36, 31
	s_mul_i32 s59, s60, 0x60000
	s_mul_hi_i32 s63, s36, 0x3000
	s_add_u32 s42, s42, s59
	v_or3_b32 v2, v215, v7, s62
	s_addc_u32 s43, s43, s63
	s_lshr_b32 s3, s3, 6
	v_mul_lo_u32 v2, v2, s52
	s_or_b32 s59, s3, 3
	v_or_b32_e32 v8, v2, v216
	v_lshl_add_u64 v[2:3], s[42:43], 0, v[194:195]
	s_mov_b64 s[42:43], 0x30000
	s_cmp_lg_u32 0, -1
	v_lshl_add_u64 v[4:5], v[2:3], 0, s[42:43]
	s_movk_i32 s42, 0x1000
	s_cselect_b32 s3, 0, 0
	v_mul_lo_u32 v0, v0, s50
	s_add_i32 s42, s3, s57
	v_or_b32_e32 v6, v0, v213
	v_or_b32_e32 v0, v0, v228
	global_load_dwordx4 v[162:165], v[2:3], off
	global_load_dwordx4 v[166:169], v[2:3], off offset:64
	global_load_dwordx4 v[170:173], v[2:3], off offset:128
	global_load_dwordx4 v[174:177], v[2:3], off offset:192
	global_load_dwordx4 v[178:181], v[4:5], off
	global_load_dwordx4 v[182:185], v[4:5], off offset:64
	global_load_dwordx4 v[186:189], v[4:5], off offset:128
	global_load_dwordx4 v[190:193], v[4:5], off offset:192
	s_add_i32 m0, s42, 0x10000
	v_add_u32_e32 v0, 0xc000, v0
	global_load_lds_dwordx4 v6, s[40:41]
	s_add_i32 m0, s42, 0x10400
	s_add_i32 s3, s58, s3
	global_load_lds_dwordx4 v0, s[40:41]
	s_mul_i32 s73, s60, 0x18000
	v_add_u32_e32 v0, s73, v220
	v_lshl_add_u64 v[2:3], s[8:9], 0, v[0:1]
	s_mov_b32 m0, s3
	s_mov_b64 s[40:41], 0x80
	global_load_lds_dwordx4 v0, s[8:9]
	v_lshl_add_u64 v[4:5], v[2:3], 0, s[40:41]
	s_add_i32 m0, s3, 0x400
	v_add3_u32 v0, v215, v7, s62
	global_load_lds_dwordx4 v[4:5], off
	v_lshl_add_u64 v[4:5], v[2:3], 0, s[10:11]
	s_add_i32 m0, s3, 0x800
	v_lshl_add_u64 v[2:3], v[2:3], 0, s[12:13]
	global_load_lds_dwordx4 v[4:5], off
	s_add_i32 m0, s3, 0xc00
	v_mul_lo_u32 v0, v0, s52
	global_load_lds_dwordx4 v[2:3], off
	v_or_b32_e32 v0, v216, v0
	v_readlane_b32 s40, v251, 40
	v_lshlrev_b32_e32 v0, 1, v0
	v_readlane_b32 s41, v251, 41
	s_mul_i32 s60, s60, 0x18000
	v_mov_b32_e32 v14, v1
	v_add_u32_e32 v0, s60, v220
	v_lshl_add_u64 v[196:197], s[40:41], 0, v[0:1]
	v_add3_u32 v0, v226, s60, v228
	v_lshl_add_u64 v[198:199], s[38:39], 0, v[0:1]
	v_add_u32_e32 v0, s60, v227
	v_mov_b32_e32 v15, v1
	s_waitcnt vmcnt(0)
	v_lshl_add_u64 v[200:201], s[38:39], 0, v[0:1]
	v_mov_b32_e32 v0, v1
	v_mov_b32_e32 v2, v1
	v_mov_b32_e32 v3, v1
	v_mov_b32_e32 v4, v1
	v_mov_b32_e32 v5, v1
	v_mov_b32_e32 v6, v1
	v_mov_b32_e32 v7, v1
	v_mov_b32_e32 v8, v1
	v_mov_b32_e32 v9, v1
	v_mov_b32_e32 v10, v1
	v_mov_b32_e32 v11, v1
	v_mov_b32_e32 v12, v1
	v_mov_b32_e32 v13, v1
	s_waitcnt vmcnt(0)
	v_mov_b64_e32 v[128:129], v[14:15]
	v_mov_b64_e32 v[112:113], v[14:15]
	v_mov_b64_e32 v[96:97], v[14:15]
	v_mov_b64_e32 v[80:81], v[14:15]
	v_mov_b64_e32 v[64:65], v[14:15]
	v_mov_b64_e32 v[48:49], v[14:15]
	v_mov_b64_e32 v[32:33], v[14:15]
	v_readlane_b32 s65, v251, 33
	v_mov_b64_e32 v[126:127], v[12:13]
	v_mov_b64_e32 v[124:125], v[10:11]
	v_mov_b64_e32 v[122:123], v[8:9]
	v_mov_b64_e32 v[120:121], v[6:7]
	v_mov_b64_e32 v[118:119], v[4:5]
	v_mov_b64_e32 v[116:117], v[2:3]
	v_mov_b64_e32 v[114:115], v[0:1]
	v_mov_b64_e32 v[110:111], v[12:13]
	v_mov_b64_e32 v[108:109], v[10:11]
	v_mov_b64_e32 v[106:107], v[8:9]
	v_mov_b64_e32 v[104:105], v[6:7]
	v_mov_b64_e32 v[102:103], v[4:5]
	v_mov_b64_e32 v[100:101], v[2:3]
	v_mov_b64_e32 v[98:99], v[0:1]
	v_mov_b64_e32 v[94:95], v[12:13]
	v_mov_b64_e32 v[92:93], v[10:11]
	v_mov_b64_e32 v[90:91], v[8:9]
	v_mov_b64_e32 v[88:89], v[6:7]
	v_mov_b64_e32 v[86:87], v[4:5]
	v_mov_b64_e32 v[84:85], v[2:3]
	v_mov_b64_e32 v[82:83], v[0:1]
	v_mov_b64_e32 v[78:79], v[12:13]
	v_mov_b64_e32 v[76:77], v[10:11]
	v_mov_b64_e32 v[74:75], v[8:9]
	v_mov_b64_e32 v[72:73], v[6:7]
	v_mov_b64_e32 v[70:71], v[4:5]
	v_mov_b64_e32 v[68:69], v[2:3]
	v_mov_b64_e32 v[66:67], v[0:1]
	v_mov_b64_e32 v[62:63], v[12:13]
	v_mov_b64_e32 v[60:61], v[10:11]
	v_mov_b64_e32 v[58:59], v[8:9]
	v_mov_b64_e32 v[56:57], v[6:7]
	v_mov_b64_e32 v[54:55], v[4:5]
	v_mov_b64_e32 v[52:53], v[2:3]
	v_mov_b64_e32 v[50:51], v[0:1]
	v_mov_b64_e32 v[46:47], v[12:13]
	v_mov_b64_e32 v[44:45], v[10:11]
	v_mov_b64_e32 v[42:43], v[8:9]
	v_mov_b64_e32 v[40:41], v[6:7]
	v_mov_b64_e32 v[38:39], v[4:5]
	v_mov_b64_e32 v[36:37], v[2:3]
	v_mov_b64_e32 v[34:35], v[0:1]
	v_mov_b64_e32 v[30:31], v[12:13]
	v_mov_b64_e32 v[28:29], v[10:11]
	v_mov_b64_e32 v[26:27], v[8:9]
	v_mov_b64_e32 v[24:25], v[6:7]
	v_mov_b64_e32 v[22:23], v[4:5]
	v_mov_b64_e32 v[20:21], v[2:3]
	v_mov_b64_e32 v[18:19], v[0:1]
	v_mov_b64_e32 v[16:17], v[14:15]
	s_mov_b32 s3, s65
	v_add_u32_e32 v233, s4, v221
	v_and_b32_e32 v232, 15, v209
	v_lshl_add_u32 v232, v232, 2, s61
	v_lshl_add_u32 v231, v212, 4, s61
	v_mov_b32_e32 v237, 0xf149f2ca
	s_movk_i32 s60, 0x7f
	s_mov_b64 s[38:39], s[6:7]
	s_mov_b32 s61, 2
	v_mov_b64_e32 v[14:15], v[12:13]
	v_mov_b64_e32 v[12:13], v[10:11]
	v_mov_b64_e32 v[10:11], v[8:9]
	v_mov_b64_e32 v[8:9], v[6:7]
	v_mov_b64_e32 v[6:7], v[4:5]
	v_mov_b64_e32 v[4:5], v[2:3]
	v_mov_b64_e32 v[2:3], v[0:1]
	v_mov_b32_e32 v0, 0
	v_mov_b32_e32 v222, 0xf149f2ca
	v_mov_b32_e32 v223, 0
	v_mov_b32_e32 v225, 0xf149f2ca
	v_mov_b32_e32 v236, 0xf149f2ca
	s_waitcnt lgkmcnt(0)
	s_barrier
	s_branch .LBB0_2408

.LBB0_2423:
	v_mov_b32_e32 v246, v0
	v_mov_b32_e32 v247, v223
	s_nop 1
	v_permlane16_swap_b32_e32 v0, v246
	v_permlane16_swap_b32_e32 v223, v247
	v_add_f32_e32 v0, v0, v246
	v_add_f32_e32 v223, v223, v247
	v_mov_b32_e32 v246, v0
	v_mov_b32_e32 v247, v223
	s_nop 1
	v_permlane32_swap_b32_e32 v0, v246
	v_permlane32_swap_b32_e32 v223, v247
	v_add_f32_e32 v0, v0, v246
	v_add_f32_e32 v223, v223, v247
	s_nop 1
	s_and_saveexec_b64 s[38:39], s[0:1]
	ds_write_b32 v232, v0
	ds_write_b32 v232, v223 offset:64
	s_or_b64 exec, exec, s[38:39]
	s_waitcnt lgkmcnt(0)
	ds_read_b128 v[146:149], v231
	ds_read_b128 v[150:153], v231 offset:64
	s_lshl_b64 s[2:3], s[2:3], 12
	s_add_u32 s2, s46, s2
	s_addc_u32 s3, s47, s3
	s_lshl_b32 s4, s56, 9
	s_add_u32 s4, s2, s4
	s_addc_u32 s38, s3, 0
	s_lshl_b64 s[2:3], s[36:37], 12
	s_add_u32 s36, s4, s2
	s_addc_u32 s37, s38, s3
	v_mbcnt_lo_u32_b32 v202, -1, 0
	v_mbcnt_hi_u32_b32 v202, -1, v202
	v_and_b32_e32 v203, 15, v202
	v_lshrrev_b32_e32 v204, 4, v202
	v_lshlrev_b32_e32 v204, 14, v204
	v_lshl_or_b32 v204, v203, 1, v204
	v_and_b32_e32 v203, 1, v202
	v_cmp_eq_u32_e64 s[76:77], 0, v203
	s_waitcnt lgkmcnt(0)
	v_rcp_f32_e32 v146, v146
	v_rcp_f32_e32 v147, v147
	v_rcp_f32_e32 v148, v148
	v_rcp_f32_e32 v149, v149
	v_rcp_f32_e32 v150, v150
	v_rcp_f32_e32 v151, v151
	v_rcp_f32_e32 v152, v152
	v_rcp_f32_e32 v153, v153
	s_nop 0
	v_mov_b32_e32 v205, v204
	v_mul_f32_e32 v2, v2, v146
	v_mul_f32_e32 v6, v6, v146
	v_mul_f32_e32 v10, v10, v146
	v_mul_f32_e32 v14, v14, v146
	v_mul_f32_e32 v18, v18, v146
	v_mul_f32_e32 v22, v22, v146
	v_mul_f32_e32 v26, v26, v146
	v_mul_f32_e32 v30, v30, v146
	v_mul_f32_e32 v34, v34, v146
	v_mul_f32_e32 v38, v38, v146
	v_mul_f32_e32 v42, v42, v146
	v_mul_f32_e32 v46, v46, v146
	v_mul_f32_e32 v50, v50, v146
	v_mul_f32_e32 v54, v54, v146
	v_mul_f32_e32 v58, v58, v146
	v_mul_f32_e32 v62, v62, v146
	v_mov_b32_dpp v162, v2 quad_perm:[1,0,3,2] row_mask:0xf bank_mask:0xf
	v_mov_b32_dpp v163, v6 quad_perm:[1,0,3,2] row_mask:0xf bank_mask:0xf
	v_mov_b32_dpp v164, v10 quad_perm:[1,0,3,2] row_mask:0xf bank_mask:0xf
	v_mov_b32_dpp v165, v14 quad_perm:[1,0,3,2] row_mask:0xf bank_mask:0xf
	v_mov_b32_dpp v166, v18 quad_perm:[1,0,3,2] row_mask:0xf bank_mask:0xf
	v_mov_b32_dpp v167, v22 quad_perm:[1,0,3,2] row_mask:0xf bank_mask:0xf
	v_mov_b32_dpp v168, v26 quad_perm:[1,0,3,2] row_mask:0xf bank_mask:0xf
	v_mov_b32_dpp v169, v30 quad_perm:[1,0,3,2] row_mask:0xf bank_mask:0xf
	v_mov_b32_dpp v170, v34 quad_perm:[1,0,3,2] row_mask:0xf bank_mask:0xf
	v_mov_b32_dpp v171, v38 quad_perm:[1,0,3,2] row_mask:0xf bank_mask:0xf
	v_mov_b32_dpp v172, v42 quad_perm:[1,0,3,2] row_mask:0xf bank_mask:0xf
	v_mov_b32_dpp v173, v46 quad_perm:[1,0,3,2] row_mask:0xf bank_mask:0xf
	v_mov_b32_dpp v174, v50 quad_perm:[1,0,3,2] row_mask:0xf bank_mask:0xf
	v_mov_b32_dpp v175, v54 quad_perm:[1,0,3,2] row_mask:0xf bank_mask:0xf
	v_mov_b32_dpp v176, v58 quad_perm:[1,0,3,2] row_mask:0xf bank_mask:0xf
	v_mov_b32_dpp v177, v62 quad_perm:[1,0,3,2] row_mask:0xf bank_mask:0xf
	v_cvt_pk_bf16_f32 v2, v2, v162
	v_cvt_pk_bf16_f32 v6, v6, v163
	v_cvt_pk_bf16_f32 v10, v10, v164
	v_cvt_pk_bf16_f32 v14, v14, v165
	v_cvt_pk_bf16_f32 v18, v18, v166
	v_cvt_pk_bf16_f32 v22, v22, v167
	v_cvt_pk_bf16_f32 v26, v26, v168
	v_cvt_pk_bf16_f32 v30, v30, v169
	v_cvt_pk_bf16_f32 v34, v34, v170
	v_cvt_pk_bf16_f32 v38, v38, v171
	v_cvt_pk_bf16_f32 v42, v42, v172
	v_cvt_pk_bf16_f32 v46, v46, v173
	v_cvt_pk_bf16_f32 v50, v50, v174
	v_cvt_pk_bf16_f32 v54, v54, v175
	v_cvt_pk_bf16_f32 v58, v58, v176
	v_cvt_pk_bf16_f32 v62, v62, v177
	s_mov_b64 exec, s[76:77]
	global_store_dword v205, v2, s[36:37] offset:0
	global_store_dword v205, v6, s[36:37] offset:32
	global_store_dword v205, v10, s[36:37] offset:64
	global_store_dword v205, v14, s[36:37] offset:96
	global_store_dword v205, v18, s[36:37] offset:128
	global_store_dword v205, v22, s[36:37] offset:160
	global_store_dword v205, v26, s[36:37] offset:192
	global_store_dword v205, v30, s[36:37] offset:224
	global_store_dword v205, v34, s[36:37] offset:256
	global_store_dword v205, v38, s[36:37] offset:288
	global_store_dword v205, v42, s[36:37] offset:320
	global_store_dword v205, v46, s[36:37] offset:352
	global_store_dword v205, v50, s[36:37] offset:384
	global_store_dword v205, v54, s[36:37] offset:416
	global_store_dword v205, v58, s[36:37] offset:448
	global_store_dword v205, v62, s[36:37] offset:480
	s_mov_b64 exec, -1
	v_add_u32_e32 v205, 0x1000, v204
	v_mul_f32_e32 v3, v3, v147
	v_mul_f32_e32 v7, v7, v147
	v_mul_f32_e32 v11, v11, v147
	v_mul_f32_e32 v15, v15, v147
	v_mul_f32_e32 v19, v19, v147
	v_mul_f32_e32 v23, v23, v147
	v_mul_f32_e32 v27, v27, v147
	v_mul_f32_e32 v31, v31, v147
	v_mul_f32_e32 v35, v35, v147
	v_mul_f32_e32 v39, v39, v147
	v_mul_f32_e32 v43, v43, v147
	v_mul_f32_e32 v47, v47, v147
	v_mul_f32_e32 v51, v51, v147
	v_mul_f32_e32 v55, v55, v147
	v_mul_f32_e32 v59, v59, v147
	v_mul_f32_e32 v63, v63, v147
	v_mov_b32_dpp v162, v3 quad_perm:[1,0,3,2] row_mask:0xf bank_mask:0xf
	v_mov_b32_dpp v163, v7 quad_perm:[1,0,3,2] row_mask:0xf bank_mask:0xf
	v_mov_b32_dpp v164, v11 quad_perm:[1,0,3,2] row_mask:0xf bank_mask:0xf
	v_mov_b32_dpp v165, v15 quad_perm:[1,0,3,2] row_mask:0xf bank_mask:0xf
	v_mov_b32_dpp v166, v19 quad_perm:[1,0,3,2] row_mask:0xf bank_mask:0xf
	v_mov_b32_dpp v167, v23 quad_perm:[1,0,3,2] row_mask:0xf bank_mask:0xf
	v_mov_b32_dpp v168, v27 quad_perm:[1,0,3,2] row_mask:0xf bank_mask:0xf
	v_mov_b32_dpp v169, v31 quad_perm:[1,0,3,2] row_mask:0xf bank_mask:0xf
	v_mov_b32_dpp v170, v35 quad_perm:[1,0,3,2] row_mask:0xf bank_mask:0xf
	v_mov_b32_dpp v171, v39 quad_perm:[1,0,3,2] row_mask:0xf bank_mask:0xf
	v_mov_b32_dpp v172, v43 quad_perm:[1,0,3,2] row_mask:0xf bank_mask:0xf
	v_mov_b32_dpp v173, v47 quad_perm:[1,0,3,2] row_mask:0xf bank_mask:0xf
	v_mov_b32_dpp v174, v51 quad_perm:[1,0,3,2] row_mask:0xf bank_mask:0xf
	v_mov_b32_dpp v175, v55 quad_perm:[1,0,3,2] row_mask:0xf bank_mask:0xf
	v_mov_b32_dpp v176, v59 quad_perm:[1,0,3,2] row_mask:0xf bank_mask:0xf
	v_mov_b32_dpp v177, v63 quad_perm:[1,0,3,2] row_mask:0xf bank_mask:0xf
	v_cvt_pk_bf16_f32 v3, v3, v162
	v_cvt_pk_bf16_f32 v7, v7, v163
	v_cvt_pk_bf16_f32 v11, v11, v164
	v_cvt_pk_bf16_f32 v15, v15, v165
	v_cvt_pk_bf16_f32 v19, v19, v166
	v_cvt_pk_bf16_f32 v23, v23, v167
	v_cvt_pk_bf16_f32 v27, v27, v168
	v_cvt_pk_bf16_f32 v31, v31, v169
	v_cvt_pk_bf16_f32 v35, v35, v170
	v_cvt_pk_bf16_f32 v39, v39, v171
	v_cvt_pk_bf16_f32 v43, v43, v172
	v_cvt_pk_bf16_f32 v47, v47, v173
	v_cvt_pk_bf16_f32 v51, v51, v174
	v_cvt_pk_bf16_f32 v55, v55, v175
	v_cvt_pk_bf16_f32 v59, v59, v176
	v_cvt_pk_bf16_f32 v63, v63, v177
	s_mov_b64 exec, s[76:77]
	global_store_dword v205, v3, s[36:37] offset:0
	global_store_dword v205, v7, s[36:37] offset:32
	global_store_dword v205, v11, s[36:37] offset:64
	global_store_dword v205, v15, s[36:37] offset:96
	global_store_dword v205, v19, s[36:37] offset:128
	global_store_dword v205, v23, s[36:37] offset:160
	global_store_dword v205, v27, s[36:37] offset:192
	global_store_dword v205, v31, s[36:37] offset:224
	global_store_dword v205, v35, s[36:37] offset:256
	global_store_dword v205, v39, s[36:37] offset:288
	global_store_dword v205, v43, s[36:37] offset:320
	global_store_dword v205, v47, s[36:37] offset:352
	global_store_dword v205, v51, s[36:37] offset:384
	global_store_dword v205, v55, s[36:37] offset:416
	global_store_dword v205, v59, s[36:37] offset:448
	global_store_dword v205, v63, s[36:37] offset:480
	s_mov_b64 exec, -1
	v_add_u32_e32 v205, 0x2000, v204
	v_mul_f32_e32 v4, v4, v148
	v_mul_f32_e32 v8, v8, v148
	v_mul_f32_e32 v12, v12, v148
	v_mul_f32_e32 v16, v16, v148
	v_mul_f32_e32 v20, v20, v148
	v_mul_f32_e32 v24, v24, v148
	v_mul_f32_e32 v28, v28, v148
	v_mul_f32_e32 v32, v32, v148
	v_mul_f32_e32 v36, v36, v148
	v_mul_f32_e32 v40, v40, v148
	v_mul_f32_e32 v44, v44, v148
	v_mul_f32_e32 v48, v48, v148
	v_mul_f32_e32 v52, v52, v148
	v_mul_f32_e32 v56, v56, v148
	v_mul_f32_e32 v60, v60, v148
	v_mul_f32_e32 v64, v64, v148
	v_mov_b32_dpp v162, v4 quad_perm:[1,0,3,2] row_mask:0xf bank_mask:0xf
	v_mov_b32_dpp v163, v8 quad_perm:[1,0,3,2] row_mask:0xf bank_mask:0xf
	v_mov_b32_dpp v164, v12 quad_perm:[1,0,3,2] row_mask:0xf bank_mask:0xf
	v_mov_b32_dpp v165, v16 quad_perm:[1,0,3,2] row_mask:0xf bank_mask:0xf
	v_mov_b32_dpp v166, v20 quad_perm:[1,0,3,2] row_mask:0xf bank_mask:0xf
	v_mov_b32_dpp v167, v24 quad_perm:[1,0,3,2] row_mask:0xf bank_mask:0xf
	v_mov_b32_dpp v168, v28 quad_perm:[1,0,3,2] row_mask:0xf bank_mask:0xf
	v_mov_b32_dpp v169, v32 quad_perm:[1,0,3,2] row_mask:0xf bank_mask:0xf
	v_mov_b32_dpp v170, v36 quad_perm:[1,0,3,2] row_mask:0xf bank_mask:0xf
	v_mov_b32_dpp v171, v40 quad_perm:[1,0,3,2] row_mask:0xf bank_mask:0xf
	v_mov_b32_dpp v172, v44 quad_perm:[1,0,3,2] row_mask:0xf bank_mask:0xf
	v_mov_b32_dpp v173, v48 quad_perm:[1,0,3,2] row_mask:0xf bank_mask:0xf
	v_mov_b32_dpp v174, v52 quad_perm:[1,0,3,2] row_mask:0xf bank_mask:0xf
	v_mov_b32_dpp v175, v56 quad_perm:[1,0,3,2] row_mask:0xf bank_mask:0xf
	v_mov_b32_dpp v176, v60 quad_perm:[1,0,3,2] row_mask:0xf bank_mask:0xf
	v_mov_b32_dpp v177, v64 quad_perm:[1,0,3,2] row_mask:0xf bank_mask:0xf
	v_cvt_pk_bf16_f32 v4, v4, v162
	v_cvt_pk_bf16_f32 v8, v8, v163
	v_cvt_pk_bf16_f32 v12, v12, v164
	v_cvt_pk_bf16_f32 v16, v16, v165
	v_cvt_pk_bf16_f32 v20, v20, v166
	v_cvt_pk_bf16_f32 v24, v24, v167
	v_cvt_pk_bf16_f32 v28, v28, v168
	v_cvt_pk_bf16_f32 v32, v32, v169
	v_cvt_pk_bf16_f32 v36, v36, v170
	v_cvt_pk_bf16_f32 v40, v40, v171
	v_cvt_pk_bf16_f32 v44, v44, v172
	v_cvt_pk_bf16_f32 v48, v48, v173
	v_cvt_pk_bf16_f32 v52, v52, v174
	v_cvt_pk_bf16_f32 v56, v56, v175
	v_cvt_pk_bf16_f32 v60, v60, v176
	v_cvt_pk_bf16_f32 v64, v64, v177
	s_mov_b64 exec, s[76:77]
	global_store_dword v205, v4, s[36:37] offset:0
	global_store_dword v205, v8, s[36:37] offset:32
	global_store_dword v205, v12, s[36:37] offset:64
	global_store_dword v205, v16, s[36:37] offset:96
	global_store_dword v205, v20, s[36:37] offset:128
	global_store_dword v205, v24, s[36:37] offset:160
	global_store_dword v205, v28, s[36:37] offset:192
	global_store_dword v205, v32, s[36:37] offset:224
	global_store_dword v205, v36, s[36:37] offset:256
	global_store_dword v205, v40, s[36:37] offset:288
	global_store_dword v205, v44, s[36:37] offset:320
	global_store_dword v205, v48, s[36:37] offset:352
	global_store_dword v205, v52, s[36:37] offset:384
	global_store_dword v205, v56, s[36:37] offset:416
	global_store_dword v205, v60, s[36:37] offset:448
	global_store_dword v205, v64, s[36:37] offset:480
	s_mov_b64 exec, -1
	v_add_u32_e32 v205, 0x3000, v204
	v_mul_f32_e32 v5, v5, v149
	v_mul_f32_e32 v9, v9, v149
	v_mul_f32_e32 v13, v13, v149
	v_mul_f32_e32 v17, v17, v149
	v_mul_f32_e32 v21, v21, v149
	v_mul_f32_e32 v25, v25, v149
	v_mul_f32_e32 v29, v29, v149
	v_mul_f32_e32 v33, v33, v149
	v_mul_f32_e32 v37, v37, v149
	v_mul_f32_e32 v41, v41, v149
	v_mul_f32_e32 v45, v45, v149
	v_mul_f32_e32 v49, v49, v149
	v_mul_f32_e32 v53, v53, v149
	v_mul_f32_e32 v57, v57, v149
	v_mul_f32_e32 v61, v61, v149
	v_mul_f32_e32 v65, v65, v149
	v_mov_b32_dpp v162, v5 quad_perm:[1,0,3,2] row_mask:0xf bank_mask:0xf
	v_mov_b32_dpp v163, v9 quad_perm:[1,0,3,2] row_mask:0xf bank_mask:0xf
	v_mov_b32_dpp v164, v13 quad_perm:[1,0,3,2] row_mask:0xf bank_mask:0xf
	v_mov_b32_dpp v165, v17 quad_perm:[1,0,3,2] row_mask:0xf bank_mask:0xf
	v_mov_b32_dpp v166, v21 quad_perm:[1,0,3,2] row_mask:0xf bank_mask:0xf
	v_mov_b32_dpp v167, v25 quad_perm:[1,0,3,2] row_mask:0xf bank_mask:0xf
	v_mov_b32_dpp v168, v29 quad_perm:[1,0,3,2] row_mask:0xf bank_mask:0xf
	v_mov_b32_dpp v169, v33 quad_perm:[1,0,3,2] row_mask:0xf bank_mask:0xf
	v_mov_b32_dpp v170, v37 quad_perm:[1,0,3,2] row_mask:0xf bank_mask:0xf
	v_mov_b32_dpp v171, v41 quad_perm:[1,0,3,2] row_mask:0xf bank_mask:0xf
	v_mov_b32_dpp v172, v45 quad_perm:[1,0,3,2] row_mask:0xf bank_mask:0xf
	v_mov_b32_dpp v173, v49 quad_perm:[1,0,3,2] row_mask:0xf bank_mask:0xf
	v_mov_b32_dpp v174, v53 quad_perm:[1,0,3,2] row_mask:0xf bank_mask:0xf
	v_mov_b32_dpp v175, v57 quad_perm:[1,0,3,2] row_mask:0xf bank_mask:0xf
	v_mov_b32_dpp v176, v61 quad_perm:[1,0,3,2] row_mask:0xf bank_mask:0xf
	v_mov_b32_dpp v177, v65 quad_perm:[1,0,3,2] row_mask:0xf bank_mask:0xf
	v_cvt_pk_bf16_f32 v5, v5, v162
	v_cvt_pk_bf16_f32 v9, v9, v163
	v_cvt_pk_bf16_f32 v13, v13, v164
	v_cvt_pk_bf16_f32 v17, v17, v165
	v_cvt_pk_bf16_f32 v21, v21, v166
	v_cvt_pk_bf16_f32 v25, v25, v167
	v_cvt_pk_bf16_f32 v29, v29, v168
	v_cvt_pk_bf16_f32 v33, v33, v169
	v_cvt_pk_bf16_f32 v37, v37, v170
	v_cvt_pk_bf16_f32 v41, v41, v171
	v_cvt_pk_bf16_f32 v45, v45, v172
	v_cvt_pk_bf16_f32 v49, v49, v173
	v_cvt_pk_bf16_f32 v53, v53, v174
	v_cvt_pk_bf16_f32 v57, v57, v175
	v_cvt_pk_bf16_f32 v61, v61, v176
	v_cvt_pk_bf16_f32 v65, v65, v177
	s_mov_b64 exec, s[76:77]
	global_store_dword v205, v5, s[36:37] offset:0
	global_store_dword v205, v9, s[36:37] offset:32
	global_store_dword v205, v13, s[36:37] offset:64
	global_store_dword v205, v17, s[36:37] offset:96
	global_store_dword v205, v21, s[36:37] offset:128
	global_store_dword v205, v25, s[36:37] offset:160
	global_store_dword v205, v29, s[36:37] offset:192
	global_store_dword v205, v33, s[36:37] offset:224
	global_store_dword v205, v37, s[36:37] offset:256
	global_store_dword v205, v41, s[36:37] offset:288
	global_store_dword v205, v45, s[36:37] offset:320
	global_store_dword v205, v49, s[36:37] offset:352
	global_store_dword v205, v53, s[36:37] offset:384
	global_store_dword v205, v57, s[36:37] offset:416
	global_store_dword v205, v61, s[36:37] offset:448
	global_store_dword v205, v65, s[36:37] offset:480
	s_mov_b64 exec, -1
	v_add_u32_e32 v205, 0x10000, v204
	v_mul_f32_e32 v66, v66, v150
	v_mul_f32_e32 v70, v70, v150
	v_mul_f32_e32 v74, v74, v150
	v_mul_f32_e32 v78, v78, v150
	v_mul_f32_e32 v82, v82, v150
	v_mul_f32_e32 v86, v86, v150
	v_mul_f32_e32 v90, v90, v150
	v_mul_f32_e32 v94, v94, v150
	v_mul_f32_e32 v98, v98, v150
	v_mul_f32_e32 v102, v102, v150
	v_mul_f32_e32 v106, v106, v150
	v_mul_f32_e32 v110, v110, v150
	v_mul_f32_e32 v114, v114, v150
	v_mul_f32_e32 v118, v118, v150
	v_mul_f32_e32 v122, v122, v150
	v_mul_f32_e32 v126, v126, v150
	v_mov_b32_dpp v162, v66 quad_perm:[1,0,3,2] row_mask:0xf bank_mask:0xf
	v_mov_b32_dpp v163, v70 quad_perm:[1,0,3,2] row_mask:0xf bank_mask:0xf
	v_mov_b32_dpp v164, v74 quad_perm:[1,0,3,2] row_mask:0xf bank_mask:0xf
	v_mov_b32_dpp v165, v78 quad_perm:[1,0,3,2] row_mask:0xf bank_mask:0xf
	v_mov_b32_dpp v166, v82 quad_perm:[1,0,3,2] row_mask:0xf bank_mask:0xf
	v_mov_b32_dpp v167, v86 quad_perm:[1,0,3,2] row_mask:0xf bank_mask:0xf
	v_mov_b32_dpp v168, v90 quad_perm:[1,0,3,2] row_mask:0xf bank_mask:0xf
	v_mov_b32_dpp v169, v94 quad_perm:[1,0,3,2] row_mask:0xf bank_mask:0xf
	v_mov_b32_dpp v170, v98 quad_perm:[1,0,3,2] row_mask:0xf bank_mask:0xf
	v_mov_b32_dpp v171, v102 quad_perm:[1,0,3,2] row_mask:0xf bank_mask:0xf
	v_mov_b32_dpp v172, v106 quad_perm:[1,0,3,2] row_mask:0xf bank_mask:0xf
	v_mov_b32_dpp v173, v110 quad_perm:[1,0,3,2] row_mask:0xf bank_mask:0xf
	v_mov_b32_dpp v174, v114 quad_perm:[1,0,3,2] row_mask:0xf bank_mask:0xf
	v_mov_b32_dpp v175, v118 quad_perm:[1,0,3,2] row_mask:0xf bank_mask:0xf
	v_mov_b32_dpp v176, v122 quad_perm:[1,0,3,2] row_mask:0xf bank_mask:0xf
	v_mov_b32_dpp v177, v126 quad_perm:[1,0,3,2] row_mask:0xf bank_mask:0xf
	v_cvt_pk_bf16_f32 v66, v66, v162
	v_cvt_pk_bf16_f32 v70, v70, v163
	v_cvt_pk_bf16_f32 v74, v74, v164
	v_cvt_pk_bf16_f32 v78, v78, v165
	v_cvt_pk_bf16_f32 v82, v82, v166
	v_cvt_pk_bf16_f32 v86, v86, v167
	v_cvt_pk_bf16_f32 v90, v90, v168
	v_cvt_pk_bf16_f32 v94, v94, v169
	v_cvt_pk_bf16_f32 v98, v98, v170
	v_cvt_pk_bf16_f32 v102, v102, v171
	v_cvt_pk_bf16_f32 v106, v106, v172
	v_cvt_pk_bf16_f32 v110, v110, v173
	v_cvt_pk_bf16_f32 v114, v114, v174
	v_cvt_pk_bf16_f32 v118, v118, v175
	v_cvt_pk_bf16_f32 v122, v122, v176
	v_cvt_pk_bf16_f32 v126, v126, v177
	s_mov_b64 exec, s[76:77]
	global_store_dword v205, v66, s[36:37] offset:0
	global_store_dword v205, v70, s[36:37] offset:32
	global_store_dword v205, v74, s[36:37] offset:64
	global_store_dword v205, v78, s[36:37] offset:96
	global_store_dword v205, v82, s[36:37] offset:128
	global_store_dword v205, v86, s[36:37] offset:160
	global_store_dword v205, v90, s[36:37] offset:192
	global_store_dword v205, v94, s[36:37] offset:224
	global_store_dword v205, v98, s[36:37] offset:256
	global_store_dword v205, v102, s[36:37] offset:288
	global_store_dword v205, v106, s[36:37] offset:320
	global_store_dword v205, v110, s[36:37] offset:352
	global_store_dword v205, v114, s[36:37] offset:384
	global_store_dword v205, v118, s[36:37] offset:416
	global_store_dword v205, v122, s[36:37] offset:448
	global_store_dword v205, v126, s[36:37] offset:480
	s_mov_b64 exec, -1
	v_add_u32_e32 v205, 0x11000, v204
	v_mul_f32_e32 v67, v67, v151
	v_mul_f32_e32 v71, v71, v151
	v_mul_f32_e32 v75, v75, v151
	v_mul_f32_e32 v79, v79, v151
	v_mul_f32_e32 v83, v83, v151
	v_mul_f32_e32 v87, v87, v151
	v_mul_f32_e32 v91, v91, v151
	v_mul_f32_e32 v95, v95, v151
	v_mul_f32_e32 v99, v99, v151
	v_mul_f32_e32 v103, v103, v151
	v_mul_f32_e32 v107, v107, v151
	v_mul_f32_e32 v111, v111, v151
	v_mul_f32_e32 v115, v115, v151
	v_mul_f32_e32 v119, v119, v151
	v_mul_f32_e32 v123, v123, v151
	v_mul_f32_e32 v127, v127, v151
	v_mov_b32_dpp v162, v67 quad_perm:[1,0,3,2] row_mask:0xf bank_mask:0xf
	v_mov_b32_dpp v163, v71 quad_perm:[1,0,3,2] row_mask:0xf bank_mask:0xf
	v_mov_b32_dpp v164, v75 quad_perm:[1,0,3,2] row_mask:0xf bank_mask:0xf
	v_mov_b32_dpp v165, v79 quad_perm:[1,0,3,2] row_mask:0xf bank_mask:0xf
	v_mov_b32_dpp v166, v83 quad_perm:[1,0,3,2] row_mask:0xf bank_mask:0xf
	v_mov_b32_dpp v167, v87 quad_perm:[1,0,3,2] row_mask:0xf bank_mask:0xf
	v_mov_b32_dpp v168, v91 quad_perm:[1,0,3,2] row_mask:0xf bank_mask:0xf
	v_mov_b32_dpp v169, v95 quad_perm:[1,0,3,2] row_mask:0xf bank_mask:0xf
	v_mov_b32_dpp v170, v99 quad_perm:[1,0,3,2] row_mask:0xf bank_mask:0xf
	v_mov_b32_dpp v171, v103 quad_perm:[1,0,3,2] row_mask:0xf bank_mask:0xf
	v_mov_b32_dpp v172, v107 quad_perm:[1,0,3,2] row_mask:0xf bank_mask:0xf
	v_mov_b32_dpp v173, v111 quad_perm:[1,0,3,2] row_mask:0xf bank_mask:0xf
	v_mov_b32_dpp v174, v115 quad_perm:[1,0,3,2] row_mask:0xf bank_mask:0xf
	v_mov_b32_dpp v175, v119 quad_perm:[1,0,3,2] row_mask:0xf bank_mask:0xf
	v_mov_b32_dpp v176, v123 quad_perm:[1,0,3,2] row_mask:0xf bank_mask:0xf
	v_mov_b32_dpp v177, v127 quad_perm:[1,0,3,2] row_mask:0xf bank_mask:0xf
	v_cvt_pk_bf16_f32 v67, v67, v162
	v_cvt_pk_bf16_f32 v71, v71, v163
	v_cvt_pk_bf16_f32 v75, v75, v164
	v_cvt_pk_bf16_f32 v79, v79, v165
	v_cvt_pk_bf16_f32 v83, v83, v166
	v_cvt_pk_bf16_f32 v87, v87, v167
	v_cvt_pk_bf16_f32 v91, v91, v168
	v_cvt_pk_bf16_f32 v95, v95, v169
	v_cvt_pk_bf16_f32 v99, v99, v170
	v_cvt_pk_bf16_f32 v103, v103, v171
	v_cvt_pk_bf16_f32 v107, v107, v172
	v_cvt_pk_bf16_f32 v111, v111, v173
	v_cvt_pk_bf16_f32 v115, v115, v174
	v_cvt_pk_bf16_f32 v119, v119, v175
	v_cvt_pk_bf16_f32 v123, v123, v176
	v_cvt_pk_bf16_f32 v127, v127, v177
	s_mov_b64 exec, s[76:77]
	global_store_dword v205, v67, s[36:37] offset:0
	global_store_dword v205, v71, s[36:37] offset:32
	global_store_dword v205, v75, s[36:37] offset:64
	global_store_dword v205, v79, s[36:37] offset:96
	global_store_dword v205, v83, s[36:37] offset:128
	global_store_dword v205, v87, s[36:37] offset:160
	global_store_dword v205, v91, s[36:37] offset:192
	global_store_dword v205, v95, s[36:37] offset:224
	global_store_dword v205, v99, s[36:37] offset:256
	global_store_dword v205, v103, s[36:37] offset:288
	global_store_dword v205, v107, s[36:37] offset:320
	global_store_dword v205, v111, s[36:37] offset:352
	global_store_dword v205, v115, s[36:37] offset:384
	global_store_dword v205, v119, s[36:37] offset:416
	global_store_dword v205, v123, s[36:37] offset:448
	global_store_dword v205, v127, s[36:37] offset:480
	s_mov_b64 exec, -1
	v_add_u32_e32 v205, 0x12000, v204
	v_mul_f32_e32 v68, v68, v152
	v_mul_f32_e32 v72, v72, v152
	v_mul_f32_e32 v76, v76, v152
	v_mul_f32_e32 v80, v80, v152
	v_mul_f32_e32 v84, v84, v152
	v_mul_f32_e32 v88, v88, v152
	v_mul_f32_e32 v92, v92, v152
	v_mul_f32_e32 v96, v96, v152
	v_mul_f32_e32 v100, v100, v152
	v_mul_f32_e32 v104, v104, v152
	v_mul_f32_e32 v108, v108, v152
	v_mul_f32_e32 v112, v112, v152
	v_mul_f32_e32 v116, v116, v152
	v_mul_f32_e32 v120, v120, v152
	v_mul_f32_e32 v124, v124, v152
	v_mul_f32_e32 v128, v128, v152
	v_mov_b32_dpp v162, v68 quad_perm:[1,0,3,2] row_mask:0xf bank_mask:0xf
	v_mov_b32_dpp v163, v72 quad_perm:[1,0,3,2] row_mask:0xf bank_mask:0xf
	v_mov_b32_dpp v164, v76 quad_perm:[1,0,3,2] row_mask:0xf bank_mask:0xf
	v_mov_b32_dpp v165, v80 quad_perm:[1,0,3,2] row_mask:0xf bank_mask:0xf
	v_mov_b32_dpp v166, v84 quad_perm:[1,0,3,2] row_mask:0xf bank_mask:0xf
	v_mov_b32_dpp v167, v88 quad_perm:[1,0,3,2] row_mask:0xf bank_mask:0xf
	v_mov_b32_dpp v168, v92 quad_perm:[1,0,3,2] row_mask:0xf bank_mask:0xf
	v_mov_b32_dpp v169, v96 quad_perm:[1,0,3,2] row_mask:0xf bank_mask:0xf
	v_mov_b32_dpp v170, v100 quad_perm:[1,0,3,2] row_mask:0xf bank_mask:0xf
	v_mov_b32_dpp v171, v104 quad_perm:[1,0,3,2] row_mask:0xf bank_mask:0xf
	v_mov_b32_dpp v172, v108 quad_perm:[1,0,3,2] row_mask:0xf bank_mask:0xf
	v_mov_b32_dpp v173, v112 quad_perm:[1,0,3,2] row_mask:0xf bank_mask:0xf
	v_mov_b32_dpp v174, v116 quad_perm:[1,0,3,2] row_mask:0xf bank_mask:0xf
	v_mov_b32_dpp v175, v120 quad_perm:[1,0,3,2] row_mask:0xf bank_mask:0xf
	v_mov_b32_dpp v176, v124 quad_perm:[1,0,3,2] row_mask:0xf bank_mask:0xf
	v_mov_b32_dpp v177, v128 quad_perm:[1,0,3,2] row_mask:0xf bank_mask:0xf
	v_cvt_pk_bf16_f32 v68, v68, v162
	v_cvt_pk_bf16_f32 v72, v72, v163
	v_cvt_pk_bf16_f32 v76, v76, v164
	v_cvt_pk_bf16_f32 v80, v80, v165
	v_cvt_pk_bf16_f32 v84, v84, v166
	v_cvt_pk_bf16_f32 v88, v88, v167
	v_cvt_pk_bf16_f32 v92, v92, v168
	v_cvt_pk_bf16_f32 v96, v96, v169
	v_cvt_pk_bf16_f32 v100, v100, v170
	v_cvt_pk_bf16_f32 v104, v104, v171
	v_cvt_pk_bf16_f32 v108, v108, v172
	v_cvt_pk_bf16_f32 v112, v112, v173
	v_cvt_pk_bf16_f32 v116, v116, v174
	v_cvt_pk_bf16_f32 v120, v120, v175
	v_cvt_pk_bf16_f32 v124, v124, v176
	v_cvt_pk_bf16_f32 v128, v128, v177
	s_mov_b64 exec, s[76:77]
	global_store_dword v205, v68, s[36:37] offset:0
	global_store_dword v205, v72, s[36:37] offset:32
	global_store_dword v205, v76, s[36:37] offset:64
	global_store_dword v205, v80, s[36:37] offset:96
	global_store_dword v205, v84, s[36:37] offset:128
	global_store_dword v205, v88, s[36:37] offset:160
	global_store_dword v205, v92, s[36:37] offset:192
	global_store_dword v205, v96, s[36:37] offset:224
	global_store_dword v205, v100, s[36:37] offset:256
	global_store_dword v205, v104, s[36:37] offset:288
	global_store_dword v205, v108, s[36:37] offset:320
	global_store_dword v205, v112, s[36:37] offset:352
	global_store_dword v205, v116, s[36:37] offset:384
	global_store_dword v205, v120, s[36:37] offset:416
	global_store_dword v205, v124, s[36:37] offset:448
	global_store_dword v205, v128, s[36:37] offset:480
	s_mov_b64 exec, -1
	v_add_u32_e32 v205, 0x13000, v204
	v_mul_f32_e32 v69, v69, v153
	v_mul_f32_e32 v73, v73, v153
	v_mul_f32_e32 v77, v77, v153
	v_mul_f32_e32 v81, v81, v153
	v_mul_f32_e32 v85, v85, v153
	v_mul_f32_e32 v89, v89, v153
	v_mul_f32_e32 v93, v93, v153
	v_mul_f32_e32 v97, v97, v153
	v_mul_f32_e32 v101, v101, v153
	v_mul_f32_e32 v105, v105, v153
	v_mul_f32_e32 v109, v109, v153
	v_mul_f32_e32 v113, v113, v153
	v_mul_f32_e32 v117, v117, v153
	v_mul_f32_e32 v121, v121, v153
	v_mul_f32_e32 v125, v125, v153
	v_mul_f32_e32 v129, v129, v153
	v_mov_b32_dpp v162, v69 quad_perm:[1,0,3,2] row_mask:0xf bank_mask:0xf
	v_mov_b32_dpp v163, v73 quad_perm:[1,0,3,2] row_mask:0xf bank_mask:0xf
	v_mov_b32_dpp v164, v77 quad_perm:[1,0,3,2] row_mask:0xf bank_mask:0xf
	v_mov_b32_dpp v165, v81 quad_perm:[1,0,3,2] row_mask:0xf bank_mask:0xf
	v_mov_b32_dpp v166, v85 quad_perm:[1,0,3,2] row_mask:0xf bank_mask:0xf
	v_mov_b32_dpp v167, v89 quad_perm:[1,0,3,2] row_mask:0xf bank_mask:0xf
	v_mov_b32_dpp v168, v93 quad_perm:[1,0,3,2] row_mask:0xf bank_mask:0xf
	v_mov_b32_dpp v169, v97 quad_perm:[1,0,3,2] row_mask:0xf bank_mask:0xf
	v_mov_b32_dpp v170, v101 quad_perm:[1,0,3,2] row_mask:0xf bank_mask:0xf
	v_mov_b32_dpp v171, v105 quad_perm:[1,0,3,2] row_mask:0xf bank_mask:0xf
	v_mov_b32_dpp v172, v109 quad_perm:[1,0,3,2] row_mask:0xf bank_mask:0xf
	v_mov_b32_dpp v173, v113 quad_perm:[1,0,3,2] row_mask:0xf bank_mask:0xf
	v_mov_b32_dpp v174, v117 quad_perm:[1,0,3,2] row_mask:0xf bank_mask:0xf
	v_mov_b32_dpp v175, v121 quad_perm:[1,0,3,2] row_mask:0xf bank_mask:0xf
	v_mov_b32_dpp v176, v125 quad_perm:[1,0,3,2] row_mask:0xf bank_mask:0xf
	v_mov_b32_dpp v177, v129 quad_perm:[1,0,3,2] row_mask:0xf bank_mask:0xf
	v_cvt_pk_bf16_f32 v69, v69, v162
	v_cvt_pk_bf16_f32 v73, v73, v163
	v_cvt_pk_bf16_f32 v77, v77, v164
	v_cvt_pk_bf16_f32 v81, v81, v165
	v_cvt_pk_bf16_f32 v85, v85, v166
	v_cvt_pk_bf16_f32 v89, v89, v167
	v_cvt_pk_bf16_f32 v93, v93, v168
	v_cvt_pk_bf16_f32 v97, v97, v169
	v_cvt_pk_bf16_f32 v101, v101, v170
	v_cvt_pk_bf16_f32 v105, v105, v171
	v_cvt_pk_bf16_f32 v109, v109, v172
	v_cvt_pk_bf16_f32 v113, v113, v173
	v_cvt_pk_bf16_f32 v117, v117, v174
	v_cvt_pk_bf16_f32 v121, v121, v175
	v_cvt_pk_bf16_f32 v125, v125, v176
	v_cvt_pk_bf16_f32 v129, v129, v177
	s_mov_b64 exec, s[76:77]
	global_store_dword v205, v69, s[36:37] offset:0
	global_store_dword v205, v73, s[36:37] offset:32
	global_store_dword v205, v77, s[36:37] offset:64
	global_store_dword v205, v81, s[36:37] offset:96
	global_store_dword v205, v85, s[36:37] offset:128
	global_store_dword v205, v89, s[36:37] offset:160
	global_store_dword v205, v93, s[36:37] offset:192
	global_store_dword v205, v97, s[36:37] offset:224
	global_store_dword v205, v101, s[36:37] offset:256
	global_store_dword v205, v105, s[36:37] offset:288
	global_store_dword v205, v109, s[36:37] offset:320
	global_store_dword v205, v113, s[36:37] offset:352
	global_store_dword v205, v117, s[36:37] offset:384
	global_store_dword v205, v121, s[36:37] offset:416
	global_store_dword v205, v125, s[36:37] offset:448
	global_store_dword v205, v129, s[36:37] offset:480
	s_mov_b64 exec, -1
	s_mov_b64 s[36:37], -1
	s_branch .LBB0_2404
